# grid-barrier first-use census: 16 counter loads issued together instead of 16 serialized round trips (on top of blocked triangular inverse etc.)
# baseline (speedup 1.0000x reference)
.LBB0_281:
.LBB0_282:
	s_andn2_saveexec_b64 s[44:45], s[2:3]
	s_cbranch_execz .LBB0_296
	v_cndmask_b32_e64 v194, v244, v245, s[38:39]
	v_mov_b32_e32 v200, 0
	v_mov_b32_e32 v201, 0
	v_mov_b32_e32 v203, 0
	v_mul_u32_u24_e32 v204, 0x2280, v189
	v_add_u32_e32 v195, v194, v204
	v_mul_u32_u24_e32 v204, 0x1100, v189
	v_add_u32_e32 v204, 0x2200, v204
	v_add_u32_e32 v196, v194, v204
	s_cmp_lg_u32 s87, 0
	s_cselect_b32 s0, 0x2000, 0
	s_add_u32 s0, s0, 0x1e800
	v_lshlrev_b32_e32 v199, 2, v188
	v_lshl_add_u32 v197, v189, 11, s0
	v_sub_u32_e32 v204, 1, v189
	v_lshl_add_u32 v204, v204, 12, s0
	v_add_u32_e32 v198, v204, v199
	ds_read_b128 v[80:83], v195 offset:272
	v_cmp_eq_u32_e32 vcc, 0, v188
	s_nop 1
	v_cndmask_b32_e64 v0, 0, 1.0, vcc
	v_cmp_eq_u32_e32 vcc, 1, v188
	s_nop 1
	v_cndmask_b32_e64 v202, 0, 1.0, vcc
	s_waitcnt lgkmcnt(0)
	v_fma_f32 v146, -v0, v80, v202
	ds_read_b128 v[80:83], v195 offset:544
	v_mov_b32_e32 v1, v146
	v_cmp_eq_u32_e32 vcc, 2, v188
	s_nop 1
	v_cndmask_b32_e64 v202, 0, 1.0, vcc
	s_waitcnt lgkmcnt(0)
	v_pk_fma_f32 v[146:147], v[0:1], v[80:81], v[202:203] neg_lo:[1,0,0] neg_hi:[1,0,0]
	ds_read_b128 v[80:83], v195 offset:816
	v_add_f32_e32 v2, v146, v147
	v_cmp_eq_u32_e32 vcc, 3, v188
	s_nop 1
	v_cndmask_b32_e64 v202, 0, 1.0, vcc
	s_waitcnt lgkmcnt(0)
	v_pk_fma_f32 v[146:147], v[0:1], v[80:81], v[202:203] neg_lo:[1,0,0] neg_hi:[1,0,0]
	v_fma_f32 v148, -v2, v82, v200
	ds_read_b128 v[80:83], v195 offset:1088
	v_add_f32_e32 v150, v146, v147
	v_add_f32_e32 v3, v148, v150
	v_cmp_eq_u32_e32 vcc, 4, v188
	s_nop 1
	v_cndmask_b32_e64 v202, 0, 1.0, vcc
	s_waitcnt lgkmcnt(0)
	v_pk_fma_f32 v[146:147], v[0:1], v[80:81], v[202:203] neg_lo:[1,0,0] neg_hi:[1,0,0]
	v_pk_fma_f32 v[148:149], v[2:3], v[82:83], v[200:201] neg_lo:[1,0,0] neg_hi:[1,0,0]
	ds_read_b128 v[80:83], v195 offset:1360
	ds_read_b128 v[84:87], v195 offset:1376
	v_add_f32_e32 v150, v147, v146
	v_add_f32_e32 v151, v148, v149
	v_add_f32_e32 v4, v151, v150
	v_cmp_eq_u32_e32 vcc, 5, v188
	s_nop 1
	v_cndmask_b32_e64 v202, 0, 1.0, vcc
	s_waitcnt lgkmcnt(0)
	v_pk_fma_f32 v[146:147], v[0:1], v[80:81], v[202:203] neg_lo:[1,0,0] neg_hi:[1,0,0]
	v_pk_fma_f32 v[148:149], v[2:3], v[82:83], v[200:201] neg_lo:[1,0,0] neg_hi:[1,0,0]
	ds_read_b128 v[80:83], v195 offset:1632
	v_fma_f32 v146, -v4, v84, v146
	ds_read_b128 v[84:87], v195 offset:1648
	v_add_f32_e32 v150, v147, v146
	v_add_f32_e32 v151, v148, v149
	v_add_f32_e32 v5, v151, v150
	v_cmp_eq_u32_e32 vcc, 6, v188
	s_nop 1
	v_cndmask_b32_e64 v202, 0, 1.0, vcc
	s_waitcnt lgkmcnt(0)
	v_pk_fma_f32 v[146:147], v[0:1], v[80:81], v[202:203] neg_lo:[1,0,0] neg_hi:[1,0,0]
	v_pk_fma_f32 v[148:149], v[2:3], v[82:83], v[200:201] neg_lo:[1,0,0] neg_hi:[1,0,0]
	ds_read_b128 v[80:83], v195 offset:1904
	v_pk_fma_f32 v[146:147], v[4:5], v[84:85], v[146:147] neg_lo:[1,0,0] neg_hi:[1,0,0]
	ds_read_b128 v[84:87], v195 offset:1920
	v_add_f32_e32 v150, v147, v146
	v_add_f32_e32 v151, v148, v149
	v_add_f32_e32 v6, v151, v150
	v_cmp_eq_u32_e32 vcc, 7, v188
	s_nop 1
	v_cndmask_b32_e64 v202, 0, 1.0, vcc
	s_waitcnt lgkmcnt(0)
	v_pk_fma_f32 v[146:147], v[0:1], v[80:81], v[202:203] neg_lo:[1,0,0] neg_hi:[1,0,0]
	v_pk_fma_f32 v[148:149], v[2:3], v[82:83], v[200:201] neg_lo:[1,0,0] neg_hi:[1,0,0]
	ds_read_b128 v[80:83], v195 offset:2176
	v_pk_fma_f32 v[146:147], v[4:5], v[84:85], v[146:147] neg_lo:[1,0,0] neg_hi:[1,0,0]
	v_fma_f32 v148, -v6, v86, v148
	ds_read_b128 v[84:87], v195 offset:2192
	v_add_f32_e32 v150, v147, v146
	v_add_f32_e32 v151, v148, v149
	v_add_f32_e32 v7, v151, v150
	v_cmp_eq_u32_e32 vcc, 8, v188
	s_nop 1
	v_cndmask_b32_e64 v202, 0, 1.0, vcc
	s_waitcnt lgkmcnt(0)
	v_pk_fma_f32 v[146:147], v[0:1], v[80:81], v[202:203] neg_lo:[1,0,0] neg_hi:[1,0,0]
	v_pk_fma_f32 v[148:149], v[2:3], v[82:83], v[200:201] neg_lo:[1,0,0] neg_hi:[1,0,0]
	ds_read_b128 v[80:83], v195 offset:2448
	v_pk_fma_f32 v[146:147], v[4:5], v[84:85], v[146:147] neg_lo:[1,0,0] neg_hi:[1,0,0]
	v_pk_fma_f32 v[148:149], v[6:7], v[86:87], v[148:149] neg_lo:[1,0,0] neg_hi:[1,0,0]
	ds_read_b128 v[84:87], v195 offset:2464
	ds_read_b128 v[88:91], v195 offset:2480
	v_add_f32_e32 v150, v147, v146
	v_add_f32_e32 v151, v148, v149
	v_add_f32_e32 v8, v151, v150
	v_cmp_eq_u32_e32 vcc, 9, v188
	s_nop 1
	v_cndmask_b32_e64 v202, 0, 1.0, vcc
	s_waitcnt lgkmcnt(0)
	v_pk_fma_f32 v[146:147], v[0:1], v[80:81], v[202:203] neg_lo:[1,0,0] neg_hi:[1,0,0]
	v_pk_fma_f32 v[148:149], v[2:3], v[82:83], v[200:201] neg_lo:[1,0,0] neg_hi:[1,0,0]
	ds_read_b128 v[80:83], v195 offset:2720
	v_pk_fma_f32 v[146:147], v[4:5], v[84:85], v[146:147] neg_lo:[1,0,0] neg_hi:[1,0,0]
	v_pk_fma_f32 v[148:149], v[6:7], v[86:87], v[148:149] neg_lo:[1,0,0] neg_hi:[1,0,0]
	ds_read_b128 v[84:87], v195 offset:2736
	v_fma_f32 v146, -v8, v88, v146
	ds_read_b128 v[88:91], v195 offset:2752
	v_add_f32_e32 v150, v147, v146
	v_add_f32_e32 v151, v148, v149
	v_add_f32_e32 v9, v151, v150
	v_cmp_eq_u32_e32 vcc, 10, v188
	s_nop 1
	v_cndmask_b32_e64 v202, 0, 1.0, vcc
	s_waitcnt lgkmcnt(0)
	v_pk_fma_f32 v[146:147], v[0:1], v[80:81], v[202:203] neg_lo:[1,0,0] neg_hi:[1,0,0]
	v_pk_fma_f32 v[148:149], v[2:3], v[82:83], v[200:201] neg_lo:[1,0,0] neg_hi:[1,0,0]
	ds_read_b128 v[80:83], v195 offset:2992
	v_pk_fma_f32 v[146:147], v[4:5], v[84:85], v[146:147] neg_lo:[1,0,0] neg_hi:[1,0,0]
	v_pk_fma_f32 v[148:149], v[6:7], v[86:87], v[148:149] neg_lo:[1,0,0] neg_hi:[1,0,0]
	ds_read_b128 v[84:87], v195 offset:3008
	v_pk_fma_f32 v[146:147], v[8:9], v[88:89], v[146:147] neg_lo:[1,0,0] neg_hi:[1,0,0]
	ds_read_b128 v[88:91], v195 offset:3024
	v_add_f32_e32 v150, v147, v146
	v_add_f32_e32 v151, v148, v149
	v_add_f32_e32 v10, v151, v150
	v_cmp_eq_u32_e32 vcc, 11, v188
	s_nop 1
	v_cndmask_b32_e64 v202, 0, 1.0, vcc
	s_waitcnt lgkmcnt(0)
	v_pk_fma_f32 v[146:147], v[0:1], v[80:81], v[202:203] neg_lo:[1,0,0] neg_hi:[1,0,0]
	v_pk_fma_f32 v[148:149], v[2:3], v[82:83], v[200:201] neg_lo:[1,0,0] neg_hi:[1,0,0]
	ds_read_b128 v[80:83], v195 offset:3264
	v_pk_fma_f32 v[146:147], v[4:5], v[84:85], v[146:147] neg_lo:[1,0,0] neg_hi:[1,0,0]
	v_pk_fma_f32 v[148:149], v[6:7], v[86:87], v[148:149] neg_lo:[1,0,0] neg_hi:[1,0,0]
	ds_read_b128 v[84:87], v195 offset:3280
	v_pk_fma_f32 v[146:147], v[8:9], v[88:89], v[146:147] neg_lo:[1,0,0] neg_hi:[1,0,0]
	v_fma_f32 v148, -v10, v90, v148
	ds_read_b128 v[88:91], v195 offset:3296
	v_add_f32_e32 v150, v147, v146
	v_add_f32_e32 v151, v148, v149
	v_add_f32_e32 v11, v151, v150
	v_cmp_eq_u32_e32 vcc, 12, v188
	s_nop 1
	v_cndmask_b32_e64 v202, 0, 1.0, vcc
	s_waitcnt lgkmcnt(0)
	v_pk_fma_f32 v[146:147], v[0:1], v[80:81], v[202:203] neg_lo:[1,0,0] neg_hi:[1,0,0]
	v_pk_fma_f32 v[148:149], v[2:3], v[82:83], v[200:201] neg_lo:[1,0,0] neg_hi:[1,0,0]
	ds_read_b128 v[80:83], v195 offset:3536
	v_pk_fma_f32 v[146:147], v[4:5], v[84:85], v[146:147] neg_lo:[1,0,0] neg_hi:[1,0,0]
	v_pk_fma_f32 v[148:149], v[6:7], v[86:87], v[148:149] neg_lo:[1,0,0] neg_hi:[1,0,0]
	ds_read_b128 v[84:87], v195 offset:3552
	v_pk_fma_f32 v[146:147], v[8:9], v[88:89], v[146:147] neg_lo:[1,0,0] neg_hi:[1,0,0]
	v_pk_fma_f32 v[148:149], v[10:11], v[90:91], v[148:149] neg_lo:[1,0,0] neg_hi:[1,0,0]
	ds_read_b128 v[88:91], v195 offset:3568
	ds_read_b128 v[92:95], v195 offset:3584
	v_add_f32_e32 v150, v147, v146
	v_add_f32_e32 v151, v148, v149
	v_add_f32_e32 v12, v151, v150
	v_cmp_eq_u32_e32 vcc, 13, v188
	s_nop 1
	v_cndmask_b32_e64 v202, 0, 1.0, vcc
	s_waitcnt lgkmcnt(0)
	v_pk_fma_f32 v[146:147], v[0:1], v[80:81], v[202:203] neg_lo:[1,0,0] neg_hi:[1,0,0]
	v_pk_fma_f32 v[148:149], v[2:3], v[82:83], v[200:201] neg_lo:[1,0,0] neg_hi:[1,0,0]
	ds_read_b128 v[80:83], v195 offset:3808
	v_pk_fma_f32 v[146:147], v[4:5], v[84:85], v[146:147] neg_lo:[1,0,0] neg_hi:[1,0,0]
	v_pk_fma_f32 v[148:149], v[6:7], v[86:87], v[148:149] neg_lo:[1,0,0] neg_hi:[1,0,0]
	ds_read_b128 v[84:87], v195 offset:3824
	v_pk_fma_f32 v[146:147], v[8:9], v[88:89], v[146:147] neg_lo:[1,0,0] neg_hi:[1,0,0]
	v_pk_fma_f32 v[148:149], v[10:11], v[90:91], v[148:149] neg_lo:[1,0,0] neg_hi:[1,0,0]
	ds_read_b128 v[88:91], v195 offset:3840
	v_fma_f32 v146, -v12, v92, v146
	ds_read_b128 v[92:95], v195 offset:3856
	v_add_f32_e32 v150, v147, v146
	v_add_f32_e32 v151, v148, v149
	v_add_f32_e32 v13, v151, v150
	v_cmp_eq_u32_e32 vcc, 14, v188
	s_nop 1
	v_cndmask_b32_e64 v202, 0, 1.0, vcc
	s_waitcnt lgkmcnt(0)
	v_pk_fma_f32 v[146:147], v[0:1], v[80:81], v[202:203] neg_lo:[1,0,0] neg_hi:[1,0,0]
	v_pk_fma_f32 v[148:149], v[2:3], v[82:83], v[200:201] neg_lo:[1,0,0] neg_hi:[1,0,0]
	ds_read_b128 v[80:83], v195 offset:4080
	v_pk_fma_f32 v[146:147], v[4:5], v[84:85], v[146:147] neg_lo:[1,0,0] neg_hi:[1,0,0]
	v_pk_fma_f32 v[148:149], v[6:7], v[86:87], v[148:149] neg_lo:[1,0,0] neg_hi:[1,0,0]
	ds_read_b128 v[84:87], v195 offset:4096
	v_pk_fma_f32 v[146:147], v[8:9], v[88:89], v[146:147] neg_lo:[1,0,0] neg_hi:[1,0,0]
	v_pk_fma_f32 v[148:149], v[10:11], v[90:91], v[148:149] neg_lo:[1,0,0] neg_hi:[1,0,0]
	ds_read_b128 v[88:91], v195 offset:4112
	v_pk_fma_f32 v[146:147], v[12:13], v[92:93], v[146:147] neg_lo:[1,0,0] neg_hi:[1,0,0]
	ds_read_b128 v[92:95], v195 offset:4128
	v_add_f32_e32 v150, v147, v146
	v_add_f32_e32 v151, v148, v149
	v_add_f32_e32 v14, v151, v150
	v_cmp_eq_u32_e32 vcc, 15, v188
	s_nop 1
	v_cndmask_b32_e64 v202, 0, 1.0, vcc
	s_waitcnt lgkmcnt(0)
	v_pk_fma_f32 v[146:147], v[0:1], v[80:81], v[202:203] neg_lo:[1,0,0] neg_hi:[1,0,0]
	v_pk_fma_f32 v[148:149], v[2:3], v[82:83], v[200:201] neg_lo:[1,0,0] neg_hi:[1,0,0]
	ds_read_b128 v[80:83], v195 offset:4352
	v_pk_fma_f32 v[146:147], v[4:5], v[84:85], v[146:147] neg_lo:[1,0,0] neg_hi:[1,0,0]
	v_pk_fma_f32 v[148:149], v[6:7], v[86:87], v[148:149] neg_lo:[1,0,0] neg_hi:[1,0,0]
	ds_read_b128 v[84:87], v195 offset:4368
	v_pk_fma_f32 v[146:147], v[8:9], v[88:89], v[146:147] neg_lo:[1,0,0] neg_hi:[1,0,0]
	v_pk_fma_f32 v[148:149], v[10:11], v[90:91], v[148:149] neg_lo:[1,0,0] neg_hi:[1,0,0]
	ds_read_b128 v[88:91], v195 offset:4384
	v_pk_fma_f32 v[146:147], v[12:13], v[92:93], v[146:147] neg_lo:[1,0,0] neg_hi:[1,0,0]
	v_fma_f32 v148, -v14, v94, v148
	ds_read_b128 v[92:95], v195 offset:4400
	v_add_f32_e32 v150, v147, v146
	v_add_f32_e32 v151, v148, v149
	v_add_f32_e32 v15, v151, v150
	v_cmp_eq_u32_e32 vcc, 16, v188
	s_nop 1
	v_cndmask_b32_e64 v202, 0, 1.0, vcc
	s_waitcnt lgkmcnt(0)
	v_pk_fma_f32 v[146:147], v[0:1], v[80:81], v[202:203] neg_lo:[1,0,0] neg_hi:[1,0,0]
	v_pk_fma_f32 v[148:149], v[2:3], v[82:83], v[200:201] neg_lo:[1,0,0] neg_hi:[1,0,0]
	ds_read_b128 v[80:83], v195 offset:4624
	v_pk_fma_f32 v[146:147], v[4:5], v[84:85], v[146:147] neg_lo:[1,0,0] neg_hi:[1,0,0]
	v_pk_fma_f32 v[148:149], v[6:7], v[86:87], v[148:149] neg_lo:[1,0,0] neg_hi:[1,0,0]
	ds_read_b128 v[84:87], v195 offset:4640
	v_pk_fma_f32 v[146:147], v[8:9], v[88:89], v[146:147] neg_lo:[1,0,0] neg_hi:[1,0,0]
	v_pk_fma_f32 v[148:149], v[10:11], v[90:91], v[148:149] neg_lo:[1,0,0] neg_hi:[1,0,0]
	ds_read_b128 v[88:91], v195 offset:4656
	v_pk_fma_f32 v[146:147], v[12:13], v[92:93], v[146:147] neg_lo:[1,0,0] neg_hi:[1,0,0]
	v_pk_fma_f32 v[148:149], v[14:15], v[94:95], v[148:149] neg_lo:[1,0,0] neg_hi:[1,0,0]
	ds_read_b128 v[92:95], v195 offset:4672
	ds_read_b128 v[96:99], v195 offset:4688
	v_add_f32_e32 v150, v147, v146
	v_add_f32_e32 v151, v148, v149
	v_add_f32_e32 v16, v151, v150
	v_cmp_eq_u32_e32 vcc, 17, v188
	s_nop 1
	v_cndmask_b32_e64 v202, 0, 1.0, vcc
	s_waitcnt lgkmcnt(1)
	v_pk_fma_f32 v[146:147], v[0:1], v[80:81], v[202:203] neg_lo:[1,0,0] neg_hi:[1,0,0]
	v_pk_fma_f32 v[148:149], v[2:3], v[82:83], v[200:201] neg_lo:[1,0,0] neg_hi:[1,0,0]
	ds_read_b128 v[80:83], v195 offset:4896
	v_pk_fma_f32 v[146:147], v[4:5], v[84:85], v[146:147] neg_lo:[1,0,0] neg_hi:[1,0,0]
	v_pk_fma_f32 v[148:149], v[6:7], v[86:87], v[148:149] neg_lo:[1,0,0] neg_hi:[1,0,0]
	ds_read_b128 v[84:87], v195 offset:4912
	v_pk_fma_f32 v[146:147], v[8:9], v[88:89], v[146:147] neg_lo:[1,0,0] neg_hi:[1,0,0]
	v_pk_fma_f32 v[148:149], v[10:11], v[90:91], v[148:149] neg_lo:[1,0,0] neg_hi:[1,0,0]
	ds_read_b128 v[88:91], v195 offset:4928
	v_pk_fma_f32 v[146:147], v[12:13], v[92:93], v[146:147] neg_lo:[1,0,0] neg_hi:[1,0,0]
	v_pk_fma_f32 v[148:149], v[14:15], v[94:95], v[148:149] neg_lo:[1,0,0] neg_hi:[1,0,0]
	ds_read_b128 v[92:95], v195 offset:4944
	s_waitcnt lgkmcnt(4)
	v_fma_f32 v146, -v16, v96, v146
	ds_read_b128 v[96:99], v195 offset:4960
	v_add_f32_e32 v150, v147, v146
	v_add_f32_e32 v151, v148, v149
	v_add_f32_e32 v17, v151, v150
	v_cmp_eq_u32_e32 vcc, 18, v188
	s_nop 1
	v_cndmask_b32_e64 v202, 0, 1.0, vcc
	s_waitcnt lgkmcnt(1)
	v_pk_fma_f32 v[146:147], v[0:1], v[80:81], v[202:203] neg_lo:[1,0,0] neg_hi:[1,0,0]
	v_pk_fma_f32 v[148:149], v[2:3], v[82:83], v[200:201] neg_lo:[1,0,0] neg_hi:[1,0,0]
	ds_read_b128 v[80:83], v195 offset:5168
	v_pk_fma_f32 v[146:147], v[4:5], v[84:85], v[146:147] neg_lo:[1,0,0] neg_hi:[1,0,0]
	v_pk_fma_f32 v[148:149], v[6:7], v[86:87], v[148:149] neg_lo:[1,0,0] neg_hi:[1,0,0]
	ds_read_b128 v[84:87], v195 offset:5184
	v_pk_fma_f32 v[146:147], v[8:9], v[88:89], v[146:147] neg_lo:[1,0,0] neg_hi:[1,0,0]
	v_pk_fma_f32 v[148:149], v[10:11], v[90:91], v[148:149] neg_lo:[1,0,0] neg_hi:[1,0,0]
	ds_read_b128 v[88:91], v195 offset:5200
	v_pk_fma_f32 v[146:147], v[12:13], v[92:93], v[146:147] neg_lo:[1,0,0] neg_hi:[1,0,0]
	v_pk_fma_f32 v[148:149], v[14:15], v[94:95], v[148:149] neg_lo:[1,0,0] neg_hi:[1,0,0]
	ds_read_b128 v[92:95], v195 offset:5216
	s_waitcnt lgkmcnt(4)
	v_pk_fma_f32 v[146:147], v[16:17], v[96:97], v[146:147] neg_lo:[1,0,0] neg_hi:[1,0,0]
	ds_read_b128 v[96:99], v195 offset:5232
	v_add_f32_e32 v150, v147, v146
	v_add_f32_e32 v151, v148, v149
	v_add_f32_e32 v18, v151, v150
	v_cmp_eq_u32_e32 vcc, 19, v188
	s_nop 1
	v_cndmask_b32_e64 v202, 0, 1.0, vcc
	s_waitcnt lgkmcnt(1)
	v_pk_fma_f32 v[146:147], v[0:1], v[80:81], v[202:203] neg_lo:[1,0,0] neg_hi:[1,0,0]
	v_pk_fma_f32 v[148:149], v[2:3], v[82:83], v[200:201] neg_lo:[1,0,0] neg_hi:[1,0,0]
	ds_read_b128 v[80:83], v195 offset:5440
	v_pk_fma_f32 v[146:147], v[4:5], v[84:85], v[146:147] neg_lo:[1,0,0] neg_hi:[1,0,0]
	v_pk_fma_f32 v[148:149], v[6:7], v[86:87], v[148:149] neg_lo:[1,0,0] neg_hi:[1,0,0]
	ds_read_b128 v[84:87], v195 offset:5456
	v_pk_fma_f32 v[146:147], v[8:9], v[88:89], v[146:147] neg_lo:[1,0,0] neg_hi:[1,0,0]
	v_pk_fma_f32 v[148:149], v[10:11], v[90:91], v[148:149] neg_lo:[1,0,0] neg_hi:[1,0,0]
	ds_read_b128 v[88:91], v195 offset:5472
	v_pk_fma_f32 v[146:147], v[12:13], v[92:93], v[146:147] neg_lo:[1,0,0] neg_hi:[1,0,0]
	v_pk_fma_f32 v[148:149], v[14:15], v[94:95], v[148:149] neg_lo:[1,0,0] neg_hi:[1,0,0]
	ds_read_b128 v[92:95], v195 offset:5488
	s_waitcnt lgkmcnt(4)
	v_pk_fma_f32 v[146:147], v[16:17], v[96:97], v[146:147] neg_lo:[1,0,0] neg_hi:[1,0,0]
	v_fma_f32 v148, -v18, v98, v148
	ds_read_b128 v[96:99], v195 offset:5504
	v_add_f32_e32 v150, v147, v146
	v_add_f32_e32 v151, v148, v149
	v_add_f32_e32 v19, v151, v150
	v_cmp_eq_u32_e32 vcc, 20, v188
	s_nop 1
	v_cndmask_b32_e64 v202, 0, 1.0, vcc
	s_waitcnt lgkmcnt(1)
	v_pk_fma_f32 v[146:147], v[0:1], v[80:81], v[202:203] neg_lo:[1,0,0] neg_hi:[1,0,0]
	v_pk_fma_f32 v[148:149], v[2:3], v[82:83], v[200:201] neg_lo:[1,0,0] neg_hi:[1,0,0]
	ds_read_b128 v[80:83], v195 offset:5712
	v_pk_fma_f32 v[146:147], v[4:5], v[84:85], v[146:147] neg_lo:[1,0,0] neg_hi:[1,0,0]
	v_pk_fma_f32 v[148:149], v[6:7], v[86:87], v[148:149] neg_lo:[1,0,0] neg_hi:[1,0,0]
	ds_read_b128 v[84:87], v195 offset:5728
	v_pk_fma_f32 v[146:147], v[8:9], v[88:89], v[146:147] neg_lo:[1,0,0] neg_hi:[1,0,0]
	v_pk_fma_f32 v[148:149], v[10:11], v[90:91], v[148:149] neg_lo:[1,0,0] neg_hi:[1,0,0]
	ds_read_b128 v[88:91], v195 offset:5744
	v_pk_fma_f32 v[146:147], v[12:13], v[92:93], v[146:147] neg_lo:[1,0,0] neg_hi:[1,0,0]
	v_pk_fma_f32 v[148:149], v[14:15], v[94:95], v[148:149] neg_lo:[1,0,0] neg_hi:[1,0,0]
	ds_read_b128 v[92:95], v195 offset:5760
	s_waitcnt lgkmcnt(4)
	v_pk_fma_f32 v[146:147], v[16:17], v[96:97], v[146:147] neg_lo:[1,0,0] neg_hi:[1,0,0]
	v_pk_fma_f32 v[148:149], v[18:19], v[98:99], v[148:149] neg_lo:[1,0,0] neg_hi:[1,0,0]
	ds_read_b128 v[96:99], v195 offset:5776
	ds_read_b128 v[100:103], v195 offset:5792
	v_add_f32_e32 v150, v147, v146
	v_add_f32_e32 v151, v148, v149
	v_add_f32_e32 v20, v151, v150
	v_cmp_eq_u32_e32 vcc, 21, v188
	s_nop 1
	v_cndmask_b32_e64 v202, 0, 1.0, vcc
	s_waitcnt lgkmcnt(2)
	v_pk_fma_f32 v[146:147], v[0:1], v[80:81], v[202:203] neg_lo:[1,0,0] neg_hi:[1,0,0]
	v_pk_fma_f32 v[148:149], v[2:3], v[82:83], v[200:201] neg_lo:[1,0,0] neg_hi:[1,0,0]
	ds_read_b128 v[80:83], v195 offset:5984
	v_pk_fma_f32 v[146:147], v[4:5], v[84:85], v[146:147] neg_lo:[1,0,0] neg_hi:[1,0,0]
	v_pk_fma_f32 v[148:149], v[6:7], v[86:87], v[148:149] neg_lo:[1,0,0] neg_hi:[1,0,0]
	ds_read_b128 v[84:87], v195 offset:6000
	v_pk_fma_f32 v[146:147], v[8:9], v[88:89], v[146:147] neg_lo:[1,0,0] neg_hi:[1,0,0]
	v_pk_fma_f32 v[148:149], v[10:11], v[90:91], v[148:149] neg_lo:[1,0,0] neg_hi:[1,0,0]
	ds_read_b128 v[88:91], v195 offset:6016
	v_pk_fma_f32 v[146:147], v[12:13], v[92:93], v[146:147] neg_lo:[1,0,0] neg_hi:[1,0,0]
	v_pk_fma_f32 v[148:149], v[14:15], v[94:95], v[148:149] neg_lo:[1,0,0] neg_hi:[1,0,0]
	ds_read_b128 v[92:95], v195 offset:6032
	s_waitcnt lgkmcnt(4)
	v_pk_fma_f32 v[146:147], v[16:17], v[96:97], v[146:147] neg_lo:[1,0,0] neg_hi:[1,0,0]
	v_pk_fma_f32 v[148:149], v[18:19], v[98:99], v[148:149] neg_lo:[1,0,0] neg_hi:[1,0,0]
	ds_read_b128 v[96:99], v195 offset:6048
	v_fma_f32 v146, -v20, v100, v146
	ds_read_b128 v[100:103], v195 offset:6064
	v_add_f32_e32 v150, v147, v146
	v_add_f32_e32 v151, v148, v149
	v_add_f32_e32 v21, v151, v150
	v_cmp_eq_u32_e32 vcc, 22, v188
	s_nop 1
	v_cndmask_b32_e64 v202, 0, 1.0, vcc
	s_waitcnt lgkmcnt(2)
	v_pk_fma_f32 v[146:147], v[0:1], v[80:81], v[202:203] neg_lo:[1,0,0] neg_hi:[1,0,0]
	v_pk_fma_f32 v[148:149], v[2:3], v[82:83], v[200:201] neg_lo:[1,0,0] neg_hi:[1,0,0]
	ds_read_b128 v[80:83], v195 offset:6256
	v_pk_fma_f32 v[146:147], v[4:5], v[84:85], v[146:147] neg_lo:[1,0,0] neg_hi:[1,0,0]
	v_pk_fma_f32 v[148:149], v[6:7], v[86:87], v[148:149] neg_lo:[1,0,0] neg_hi:[1,0,0]
	ds_read_b128 v[84:87], v195 offset:6272
	v_pk_fma_f32 v[146:147], v[8:9], v[88:89], v[146:147] neg_lo:[1,0,0] neg_hi:[1,0,0]
	v_pk_fma_f32 v[148:149], v[10:11], v[90:91], v[148:149] neg_lo:[1,0,0] neg_hi:[1,0,0]
	ds_read_b128 v[88:91], v195 offset:6288
	v_pk_fma_f32 v[146:147], v[12:13], v[92:93], v[146:147] neg_lo:[1,0,0] neg_hi:[1,0,0]
	v_pk_fma_f32 v[148:149], v[14:15], v[94:95], v[148:149] neg_lo:[1,0,0] neg_hi:[1,0,0]
	ds_read_b128 v[92:95], v195 offset:6304
	s_waitcnt lgkmcnt(4)
	v_pk_fma_f32 v[146:147], v[16:17], v[96:97], v[146:147] neg_lo:[1,0,0] neg_hi:[1,0,0]
	v_pk_fma_f32 v[148:149], v[18:19], v[98:99], v[148:149] neg_lo:[1,0,0] neg_hi:[1,0,0]
	ds_read_b128 v[96:99], v195 offset:6320
	v_pk_fma_f32 v[146:147], v[20:21], v[100:101], v[146:147] neg_lo:[1,0,0] neg_hi:[1,0,0]
	ds_read_b128 v[100:103], v195 offset:6336
	v_add_f32_e32 v150, v147, v146
	v_add_f32_e32 v151, v148, v149
	v_add_f32_e32 v22, v151, v150
	v_cmp_eq_u32_e32 vcc, 23, v188
	s_nop 1
	v_cndmask_b32_e64 v202, 0, 1.0, vcc
	s_waitcnt lgkmcnt(2)
	v_pk_fma_f32 v[146:147], v[0:1], v[80:81], v[202:203] neg_lo:[1,0,0] neg_hi:[1,0,0]
	v_pk_fma_f32 v[148:149], v[2:3], v[82:83], v[200:201] neg_lo:[1,0,0] neg_hi:[1,0,0]
	ds_read_b128 v[80:83], v195 offset:6528
	v_pk_fma_f32 v[146:147], v[4:5], v[84:85], v[146:147] neg_lo:[1,0,0] neg_hi:[1,0,0]
	v_pk_fma_f32 v[148:149], v[6:7], v[86:87], v[148:149] neg_lo:[1,0,0] neg_hi:[1,0,0]
	ds_read_b128 v[84:87], v195 offset:6544
	v_pk_fma_f32 v[146:147], v[8:9], v[88:89], v[146:147] neg_lo:[1,0,0] neg_hi:[1,0,0]
	v_pk_fma_f32 v[148:149], v[10:11], v[90:91], v[148:149] neg_lo:[1,0,0] neg_hi:[1,0,0]
	ds_read_b128 v[88:91], v195 offset:6560
	v_pk_fma_f32 v[146:147], v[12:13], v[92:93], v[146:147] neg_lo:[1,0,0] neg_hi:[1,0,0]
	v_pk_fma_f32 v[148:149], v[14:15], v[94:95], v[148:149] neg_lo:[1,0,0] neg_hi:[1,0,0]
	ds_read_b128 v[92:95], v195 offset:6576
	s_waitcnt lgkmcnt(4)
	v_pk_fma_f32 v[146:147], v[16:17], v[96:97], v[146:147] neg_lo:[1,0,0] neg_hi:[1,0,0]
	v_pk_fma_f32 v[148:149], v[18:19], v[98:99], v[148:149] neg_lo:[1,0,0] neg_hi:[1,0,0]
	ds_read_b128 v[96:99], v195 offset:6592
	v_pk_fma_f32 v[146:147], v[20:21], v[100:101], v[146:147] neg_lo:[1,0,0] neg_hi:[1,0,0]
	v_fma_f32 v148, -v22, v102, v148
	ds_read_b128 v[100:103], v195 offset:6608
	v_add_f32_e32 v150, v147, v146
	v_add_f32_e32 v151, v148, v149
	v_add_f32_e32 v23, v151, v150
	v_cmp_eq_u32_e32 vcc, 24, v188
	s_nop 1
	v_cndmask_b32_e64 v202, 0, 1.0, vcc
	s_waitcnt lgkmcnt(2)
	v_pk_fma_f32 v[146:147], v[0:1], v[80:81], v[202:203] neg_lo:[1,0,0] neg_hi:[1,0,0]
	v_pk_fma_f32 v[148:149], v[2:3], v[82:83], v[200:201] neg_lo:[1,0,0] neg_hi:[1,0,0]
	ds_read_b128 v[80:83], v195 offset:6800
	v_pk_fma_f32 v[146:147], v[4:5], v[84:85], v[146:147] neg_lo:[1,0,0] neg_hi:[1,0,0]
	v_pk_fma_f32 v[148:149], v[6:7], v[86:87], v[148:149] neg_lo:[1,0,0] neg_hi:[1,0,0]
	ds_read_b128 v[84:87], v195 offset:6816
	v_pk_fma_f32 v[146:147], v[8:9], v[88:89], v[146:147] neg_lo:[1,0,0] neg_hi:[1,0,0]
	v_pk_fma_f32 v[148:149], v[10:11], v[90:91], v[148:149] neg_lo:[1,0,0] neg_hi:[1,0,0]
	ds_read_b128 v[88:91], v195 offset:6832
	v_pk_fma_f32 v[146:147], v[12:13], v[92:93], v[146:147] neg_lo:[1,0,0] neg_hi:[1,0,0]
	v_pk_fma_f32 v[148:149], v[14:15], v[94:95], v[148:149] neg_lo:[1,0,0] neg_hi:[1,0,0]
	ds_read_b128 v[92:95], v195 offset:6848
	s_waitcnt lgkmcnt(4)
	v_pk_fma_f32 v[146:147], v[16:17], v[96:97], v[146:147] neg_lo:[1,0,0] neg_hi:[1,0,0]
	v_pk_fma_f32 v[148:149], v[18:19], v[98:99], v[148:149] neg_lo:[1,0,0] neg_hi:[1,0,0]
	ds_read_b128 v[96:99], v195 offset:6864
	v_pk_fma_f32 v[146:147], v[20:21], v[100:101], v[146:147] neg_lo:[1,0,0] neg_hi:[1,0,0]
	v_pk_fma_f32 v[148:149], v[22:23], v[102:103], v[148:149] neg_lo:[1,0,0] neg_hi:[1,0,0]
	ds_read_b128 v[100:103], v195 offset:6880
	ds_read_b128 v[104:107], v195 offset:6896
	v_add_f32_e32 v150, v147, v146
	v_add_f32_e32 v151, v148, v149
	v_add_f32_e32 v24, v151, v150
	v_cmp_eq_u32_e32 vcc, 25, v188
	s_nop 1
	v_cndmask_b32_e64 v202, 0, 1.0, vcc
	s_waitcnt lgkmcnt(3)
	v_pk_fma_f32 v[146:147], v[0:1], v[80:81], v[202:203] neg_lo:[1,0,0] neg_hi:[1,0,0]
	v_pk_fma_f32 v[148:149], v[2:3], v[82:83], v[200:201] neg_lo:[1,0,0] neg_hi:[1,0,0]
	ds_read_b128 v[80:83], v195 offset:7072
	v_pk_fma_f32 v[146:147], v[4:5], v[84:85], v[146:147] neg_lo:[1,0,0] neg_hi:[1,0,0]
	v_pk_fma_f32 v[148:149], v[6:7], v[86:87], v[148:149] neg_lo:[1,0,0] neg_hi:[1,0,0]
	ds_read_b128 v[84:87], v195 offset:7088
	v_pk_fma_f32 v[146:147], v[8:9], v[88:89], v[146:147] neg_lo:[1,0,0] neg_hi:[1,0,0]
	v_pk_fma_f32 v[148:149], v[10:11], v[90:91], v[148:149] neg_lo:[1,0,0] neg_hi:[1,0,0]
	ds_read_b128 v[88:91], v195 offset:7104
	v_pk_fma_f32 v[146:147], v[12:13], v[92:93], v[146:147] neg_lo:[1,0,0] neg_hi:[1,0,0]
	v_pk_fma_f32 v[148:149], v[14:15], v[94:95], v[148:149] neg_lo:[1,0,0] neg_hi:[1,0,0]
	ds_read_b128 v[92:95], v195 offset:7120
	s_waitcnt lgkmcnt(4)
	v_pk_fma_f32 v[146:147], v[16:17], v[96:97], v[146:147] neg_lo:[1,0,0] neg_hi:[1,0,0]
	v_pk_fma_f32 v[148:149], v[18:19], v[98:99], v[148:149] neg_lo:[1,0,0] neg_hi:[1,0,0]
	ds_read_b128 v[96:99], v195 offset:7136
	v_pk_fma_f32 v[146:147], v[20:21], v[100:101], v[146:147] neg_lo:[1,0,0] neg_hi:[1,0,0]
	v_pk_fma_f32 v[148:149], v[22:23], v[102:103], v[148:149] neg_lo:[1,0,0] neg_hi:[1,0,0]
	ds_read_b128 v[100:103], v195 offset:7152
	v_fma_f32 v146, -v24, v104, v146
	ds_read_b128 v[104:107], v195 offset:7168
	v_add_f32_e32 v150, v147, v146
	v_add_f32_e32 v151, v148, v149
	v_add_f32_e32 v25, v151, v150
	v_cmp_eq_u32_e32 vcc, 26, v188
	s_nop 1
	v_cndmask_b32_e64 v202, 0, 1.0, vcc
	s_waitcnt lgkmcnt(3)
	v_pk_fma_f32 v[146:147], v[0:1], v[80:81], v[202:203] neg_lo:[1,0,0] neg_hi:[1,0,0]
	v_pk_fma_f32 v[148:149], v[2:3], v[82:83], v[200:201] neg_lo:[1,0,0] neg_hi:[1,0,0]
	ds_read_b128 v[80:83], v195 offset:7344
	v_pk_fma_f32 v[146:147], v[4:5], v[84:85], v[146:147] neg_lo:[1,0,0] neg_hi:[1,0,0]
	v_pk_fma_f32 v[148:149], v[6:7], v[86:87], v[148:149] neg_lo:[1,0,0] neg_hi:[1,0,0]
	ds_read_b128 v[84:87], v195 offset:7360
	v_pk_fma_f32 v[146:147], v[8:9], v[88:89], v[146:147] neg_lo:[1,0,0] neg_hi:[1,0,0]
	v_pk_fma_f32 v[148:149], v[10:11], v[90:91], v[148:149] neg_lo:[1,0,0] neg_hi:[1,0,0]
	ds_read_b128 v[88:91], v195 offset:7376
	v_pk_fma_f32 v[146:147], v[12:13], v[92:93], v[146:147] neg_lo:[1,0,0] neg_hi:[1,0,0]
	v_pk_fma_f32 v[148:149], v[14:15], v[94:95], v[148:149] neg_lo:[1,0,0] neg_hi:[1,0,0]
	ds_read_b128 v[92:95], v195 offset:7392
	s_waitcnt lgkmcnt(4)
	v_pk_fma_f32 v[146:147], v[16:17], v[96:97], v[146:147] neg_lo:[1,0,0] neg_hi:[1,0,0]
	v_pk_fma_f32 v[148:149], v[18:19], v[98:99], v[148:149] neg_lo:[1,0,0] neg_hi:[1,0,0]
	ds_read_b128 v[96:99], v195 offset:7408
	v_pk_fma_f32 v[146:147], v[20:21], v[100:101], v[146:147] neg_lo:[1,0,0] neg_hi:[1,0,0]
	v_pk_fma_f32 v[148:149], v[22:23], v[102:103], v[148:149] neg_lo:[1,0,0] neg_hi:[1,0,0]
	ds_read_b128 v[100:103], v195 offset:7424
	v_pk_fma_f32 v[146:147], v[24:25], v[104:105], v[146:147] neg_lo:[1,0,0] neg_hi:[1,0,0]
	ds_read_b128 v[104:107], v195 offset:7440
	v_add_f32_e32 v150, v147, v146
	v_add_f32_e32 v151, v148, v149
	v_add_f32_e32 v26, v151, v150
	v_cmp_eq_u32_e32 vcc, 27, v188
	s_nop 1
	v_cndmask_b32_e64 v202, 0, 1.0, vcc
	s_waitcnt lgkmcnt(3)
	v_pk_fma_f32 v[146:147], v[0:1], v[80:81], v[202:203] neg_lo:[1,0,0] neg_hi:[1,0,0]
	v_pk_fma_f32 v[148:149], v[2:3], v[82:83], v[200:201] neg_lo:[1,0,0] neg_hi:[1,0,0]
	ds_read_b128 v[80:83], v195 offset:7616
	v_pk_fma_f32 v[146:147], v[4:5], v[84:85], v[146:147] neg_lo:[1,0,0] neg_hi:[1,0,0]
	v_pk_fma_f32 v[148:149], v[6:7], v[86:87], v[148:149] neg_lo:[1,0,0] neg_hi:[1,0,0]
	ds_read_b128 v[84:87], v195 offset:7632
	v_pk_fma_f32 v[146:147], v[8:9], v[88:89], v[146:147] neg_lo:[1,0,0] neg_hi:[1,0,0]
	v_pk_fma_f32 v[148:149], v[10:11], v[90:91], v[148:149] neg_lo:[1,0,0] neg_hi:[1,0,0]
	ds_read_b128 v[88:91], v195 offset:7648
	v_pk_fma_f32 v[146:147], v[12:13], v[92:93], v[146:147] neg_lo:[1,0,0] neg_hi:[1,0,0]
	v_pk_fma_f32 v[148:149], v[14:15], v[94:95], v[148:149] neg_lo:[1,0,0] neg_hi:[1,0,0]
	ds_read_b128 v[92:95], v195 offset:7664
	s_waitcnt lgkmcnt(4)
	v_pk_fma_f32 v[146:147], v[16:17], v[96:97], v[146:147] neg_lo:[1,0,0] neg_hi:[1,0,0]
	v_pk_fma_f32 v[148:149], v[18:19], v[98:99], v[148:149] neg_lo:[1,0,0] neg_hi:[1,0,0]
	ds_read_b128 v[96:99], v195 offset:7680
	v_pk_fma_f32 v[146:147], v[20:21], v[100:101], v[146:147] neg_lo:[1,0,0] neg_hi:[1,0,0]
	v_pk_fma_f32 v[148:149], v[22:23], v[102:103], v[148:149] neg_lo:[1,0,0] neg_hi:[1,0,0]
	ds_read_b128 v[100:103], v195 offset:7696
	v_pk_fma_f32 v[146:147], v[24:25], v[104:105], v[146:147] neg_lo:[1,0,0] neg_hi:[1,0,0]
	v_fma_f32 v148, -v26, v106, v148
	ds_read_b128 v[104:107], v195 offset:7712
	v_add_f32_e32 v150, v147, v146
	v_add_f32_e32 v151, v148, v149
	v_add_f32_e32 v27, v151, v150
	v_cmp_eq_u32_e32 vcc, 28, v188
	s_nop 1
	v_cndmask_b32_e64 v202, 0, 1.0, vcc
	s_waitcnt lgkmcnt(3)
	v_pk_fma_f32 v[146:147], v[0:1], v[80:81], v[202:203] neg_lo:[1,0,0] neg_hi:[1,0,0]
	v_pk_fma_f32 v[148:149], v[2:3], v[82:83], v[200:201] neg_lo:[1,0,0] neg_hi:[1,0,0]
	ds_read_b128 v[80:83], v195 offset:7888
	v_pk_fma_f32 v[146:147], v[4:5], v[84:85], v[146:147] neg_lo:[1,0,0] neg_hi:[1,0,0]
	v_pk_fma_f32 v[148:149], v[6:7], v[86:87], v[148:149] neg_lo:[1,0,0] neg_hi:[1,0,0]
	ds_read_b128 v[84:87], v195 offset:7904
	v_pk_fma_f32 v[146:147], v[8:9], v[88:89], v[146:147] neg_lo:[1,0,0] neg_hi:[1,0,0]
	v_pk_fma_f32 v[148:149], v[10:11], v[90:91], v[148:149] neg_lo:[1,0,0] neg_hi:[1,0,0]
	ds_read_b128 v[88:91], v195 offset:7920
	v_pk_fma_f32 v[146:147], v[12:13], v[92:93], v[146:147] neg_lo:[1,0,0] neg_hi:[1,0,0]
	v_pk_fma_f32 v[148:149], v[14:15], v[94:95], v[148:149] neg_lo:[1,0,0] neg_hi:[1,0,0]
	ds_read_b128 v[92:95], v195 offset:7936
	s_waitcnt lgkmcnt(4)
	v_pk_fma_f32 v[146:147], v[16:17], v[96:97], v[146:147] neg_lo:[1,0,0] neg_hi:[1,0,0]
	v_pk_fma_f32 v[148:149], v[18:19], v[98:99], v[148:149] neg_lo:[1,0,0] neg_hi:[1,0,0]
	ds_read_b128 v[96:99], v195 offset:7952
	v_pk_fma_f32 v[146:147], v[20:21], v[100:101], v[146:147] neg_lo:[1,0,0] neg_hi:[1,0,0]
	v_pk_fma_f32 v[148:149], v[22:23], v[102:103], v[148:149] neg_lo:[1,0,0] neg_hi:[1,0,0]
	ds_read_b128 v[100:103], v195 offset:7968
	v_pk_fma_f32 v[146:147], v[24:25], v[104:105], v[146:147] neg_lo:[1,0,0] neg_hi:[1,0,0]
	v_pk_fma_f32 v[148:149], v[26:27], v[106:107], v[148:149] neg_lo:[1,0,0] neg_hi:[1,0,0]
	ds_read_b128 v[104:107], v195 offset:7984
	ds_read_b128 v[108:111], v195 offset:8000
	v_add_f32_e32 v150, v147, v146
	v_add_f32_e32 v151, v148, v149
	v_add_f32_e32 v28, v151, v150
	v_cmp_eq_u32_e32 vcc, 29, v188
	s_nop 1
	v_cndmask_b32_e64 v202, 0, 1.0, vcc
	s_waitcnt lgkmcnt(4)
	v_pk_fma_f32 v[146:147], v[0:1], v[80:81], v[202:203] neg_lo:[1,0,0] neg_hi:[1,0,0]
	v_pk_fma_f32 v[148:149], v[2:3], v[82:83], v[200:201] neg_lo:[1,0,0] neg_hi:[1,0,0]
	ds_read_b128 v[80:83], v195 offset:8160
	v_pk_fma_f32 v[146:147], v[4:5], v[84:85], v[146:147] neg_lo:[1,0,0] neg_hi:[1,0,0]
	v_pk_fma_f32 v[148:149], v[6:7], v[86:87], v[148:149] neg_lo:[1,0,0] neg_hi:[1,0,0]
	ds_read_b128 v[84:87], v195 offset:8176
	v_pk_fma_f32 v[146:147], v[8:9], v[88:89], v[146:147] neg_lo:[1,0,0] neg_hi:[1,0,0]
	v_pk_fma_f32 v[148:149], v[10:11], v[90:91], v[148:149] neg_lo:[1,0,0] neg_hi:[1,0,0]
	ds_read_b128 v[88:91], v195 offset:8192
	v_pk_fma_f32 v[146:147], v[12:13], v[92:93], v[146:147] neg_lo:[1,0,0] neg_hi:[1,0,0]
	v_pk_fma_f32 v[148:149], v[14:15], v[94:95], v[148:149] neg_lo:[1,0,0] neg_hi:[1,0,0]
	ds_read_b128 v[92:95], v195 offset:8208
	s_waitcnt lgkmcnt(4)
	v_pk_fma_f32 v[146:147], v[16:17], v[96:97], v[146:147] neg_lo:[1,0,0] neg_hi:[1,0,0]
	v_pk_fma_f32 v[148:149], v[18:19], v[98:99], v[148:149] neg_lo:[1,0,0] neg_hi:[1,0,0]
	ds_read_b128 v[96:99], v195 offset:8224
	v_pk_fma_f32 v[146:147], v[20:21], v[100:101], v[146:147] neg_lo:[1,0,0] neg_hi:[1,0,0]
	v_pk_fma_f32 v[148:149], v[22:23], v[102:103], v[148:149] neg_lo:[1,0,0] neg_hi:[1,0,0]
	ds_read_b128 v[100:103], v195 offset:8240
	v_pk_fma_f32 v[146:147], v[24:25], v[104:105], v[146:147] neg_lo:[1,0,0] neg_hi:[1,0,0]
	v_pk_fma_f32 v[148:149], v[26:27], v[106:107], v[148:149] neg_lo:[1,0,0] neg_hi:[1,0,0]
	ds_read_b128 v[104:107], v195 offset:8256
	v_fma_f32 v146, -v28, v108, v146
	ds_read_b128 v[108:111], v195 offset:8272
	v_add_f32_e32 v150, v147, v146
	v_add_f32_e32 v151, v148, v149
	v_add_f32_e32 v29, v151, v150
	v_cmp_eq_u32_e32 vcc, 30, v188
	s_nop 1
	v_cndmask_b32_e64 v202, 0, 1.0, vcc
	s_waitcnt lgkmcnt(4)
	v_pk_fma_f32 v[146:147], v[0:1], v[80:81], v[202:203] neg_lo:[1,0,0] neg_hi:[1,0,0]
	v_pk_fma_f32 v[148:149], v[2:3], v[82:83], v[200:201] neg_lo:[1,0,0] neg_hi:[1,0,0]
	ds_read_b128 v[80:83], v195 offset:8432
	v_pk_fma_f32 v[146:147], v[4:5], v[84:85], v[146:147] neg_lo:[1,0,0] neg_hi:[1,0,0]
	v_pk_fma_f32 v[148:149], v[6:7], v[86:87], v[148:149] neg_lo:[1,0,0] neg_hi:[1,0,0]
	ds_read_b128 v[84:87], v195 offset:8448
	v_pk_fma_f32 v[146:147], v[8:9], v[88:89], v[146:147] neg_lo:[1,0,0] neg_hi:[1,0,0]
	v_pk_fma_f32 v[148:149], v[10:11], v[90:91], v[148:149] neg_lo:[1,0,0] neg_hi:[1,0,0]
	ds_read_b128 v[88:91], v195 offset:8464
	v_pk_fma_f32 v[146:147], v[12:13], v[92:93], v[146:147] neg_lo:[1,0,0] neg_hi:[1,0,0]
	v_pk_fma_f32 v[148:149], v[14:15], v[94:95], v[148:149] neg_lo:[1,0,0] neg_hi:[1,0,0]
	ds_read_b128 v[92:95], v195 offset:8480
	s_waitcnt lgkmcnt(4)
	v_pk_fma_f32 v[146:147], v[16:17], v[96:97], v[146:147] neg_lo:[1,0,0] neg_hi:[1,0,0]
	v_pk_fma_f32 v[148:149], v[18:19], v[98:99], v[148:149] neg_lo:[1,0,0] neg_hi:[1,0,0]
	ds_read_b128 v[96:99], v195 offset:8496
	v_pk_fma_f32 v[146:147], v[20:21], v[100:101], v[146:147] neg_lo:[1,0,0] neg_hi:[1,0,0]
	v_pk_fma_f32 v[148:149], v[22:23], v[102:103], v[148:149] neg_lo:[1,0,0] neg_hi:[1,0,0]
	ds_read_b128 v[100:103], v195 offset:8512
	v_pk_fma_f32 v[146:147], v[24:25], v[104:105], v[146:147] neg_lo:[1,0,0] neg_hi:[1,0,0]
	v_pk_fma_f32 v[148:149], v[26:27], v[106:107], v[148:149] neg_lo:[1,0,0] neg_hi:[1,0,0]
	ds_read_b128 v[104:107], v195 offset:8528
	v_pk_fma_f32 v[146:147], v[28:29], v[108:109], v[146:147] neg_lo:[1,0,0] neg_hi:[1,0,0]
	ds_read_b128 v[108:111], v195 offset:8544
	v_add_f32_e32 v150, v147, v146
	v_add_f32_e32 v151, v148, v149
	v_add_f32_e32 v30, v151, v150
	v_cmp_eq_u32_e32 vcc, 31, v188
	s_nop 1
	v_cndmask_b32_e64 v202, 0, 1.0, vcc
	s_waitcnt lgkmcnt(4)
	v_pk_fma_f32 v[146:147], v[0:1], v[80:81], v[202:203] neg_lo:[1,0,0] neg_hi:[1,0,0]
	v_pk_fma_f32 v[148:149], v[2:3], v[82:83], v[200:201] neg_lo:[1,0,0] neg_hi:[1,0,0]
	v_pk_fma_f32 v[146:147], v[4:5], v[84:85], v[146:147] neg_lo:[1,0,0] neg_hi:[1,0,0]
	v_pk_fma_f32 v[148:149], v[6:7], v[86:87], v[148:149] neg_lo:[1,0,0] neg_hi:[1,0,0]
	v_pk_fma_f32 v[146:147], v[8:9], v[88:89], v[146:147] neg_lo:[1,0,0] neg_hi:[1,0,0]
	v_pk_fma_f32 v[148:149], v[10:11], v[90:91], v[148:149] neg_lo:[1,0,0] neg_hi:[1,0,0]
	v_pk_fma_f32 v[146:147], v[12:13], v[92:93], v[146:147] neg_lo:[1,0,0] neg_hi:[1,0,0]
	v_pk_fma_f32 v[148:149], v[14:15], v[94:95], v[148:149] neg_lo:[1,0,0] neg_hi:[1,0,0]
	s_waitcnt lgkmcnt(0)
	v_pk_fma_f32 v[146:147], v[16:17], v[96:97], v[146:147] neg_lo:[1,0,0] neg_hi:[1,0,0]
	v_pk_fma_f32 v[148:149], v[18:19], v[98:99], v[148:149] neg_lo:[1,0,0] neg_hi:[1,0,0]
	v_pk_fma_f32 v[146:147], v[20:21], v[100:101], v[146:147] neg_lo:[1,0,0] neg_hi:[1,0,0]
	v_pk_fma_f32 v[148:149], v[22:23], v[102:103], v[148:149] neg_lo:[1,0,0] neg_hi:[1,0,0]
	v_pk_fma_f32 v[146:147], v[24:25], v[104:105], v[146:147] neg_lo:[1,0,0] neg_hi:[1,0,0]
	v_pk_fma_f32 v[148:149], v[26:27], v[106:107], v[148:149] neg_lo:[1,0,0] neg_hi:[1,0,0]
	v_pk_fma_f32 v[146:147], v[28:29], v[108:109], v[146:147] neg_lo:[1,0,0] neg_hi:[1,0,0]
	v_fma_f32 v148, -v30, v110, v148
	v_add_f32_e32 v150, v147, v146
	v_add_f32_e32 v151, v148, v149
	v_add_f32_e32 v31, v151, v150
	ds_write_b32 v198, v0
	ds_write_b32 v198, v1 offset:128
	ds_write_b32 v198, v2 offset:256
	ds_write_b32 v198, v3 offset:384
	ds_write_b32 v198, v4 offset:512
	ds_write_b32 v198, v5 offset:640
	ds_write_b32 v198, v6 offset:768
	ds_write_b32 v198, v7 offset:896
	ds_write_b32 v198, v8 offset:1024
	ds_write_b32 v198, v9 offset:1152
	ds_write_b32 v198, v10 offset:1280
	ds_write_b32 v198, v11 offset:1408
	ds_write_b32 v198, v12 offset:1536
	ds_write_b32 v198, v13 offset:1664
	ds_write_b32 v198, v14 offset:1792
	s_waitcnt lgkmcnt(14)
	ds_write_b32 v198, v15 offset:1920
	s_waitcnt lgkmcnt(14)
	ds_write_b32 v198, v16 offset:2048
	s_waitcnt lgkmcnt(14)
	ds_write_b32 v198, v17 offset:2176
	s_waitcnt lgkmcnt(14)
	ds_write_b32 v198, v18 offset:2304
	s_waitcnt lgkmcnt(14)
	ds_write_b32 v198, v19 offset:2432
	s_waitcnt lgkmcnt(14)
	ds_write_b32 v198, v20 offset:2560
	s_waitcnt lgkmcnt(14)
	ds_write_b32 v198, v21 offset:2688
	s_waitcnt lgkmcnt(14)
	ds_write_b32 v198, v22 offset:2816
	s_waitcnt lgkmcnt(14)
	ds_write_b32 v198, v23 offset:2944
	s_waitcnt lgkmcnt(14)
	ds_write_b32 v198, v24 offset:3072
	s_waitcnt lgkmcnt(14)
	ds_write_b32 v198, v25 offset:3200
	s_waitcnt lgkmcnt(14)
	ds_write_b32 v198, v26 offset:3328
	s_waitcnt lgkmcnt(14)
	ds_write_b32 v198, v27 offset:3456
	s_waitcnt lgkmcnt(14)
	ds_write_b32 v198, v28 offset:3584
	s_waitcnt lgkmcnt(14)
	ds_write_b32 v198, v29 offset:3712
	s_waitcnt lgkmcnt(14)
	ds_write_b32 v198, v30 offset:3840
	s_waitcnt lgkmcnt(14)
	ds_write_b32 v198, v31 offset:3968
	v_mov_b32_e32 v32, v0
	v_mov_b32_e32 v204, v0
	v_mov_b32_e32 v33, v1
	v_mov_b32_e32 v205, v1
	s_nop 1
	v_permlane32_swap_b32_e32 v32, v204
	v_permlane32_swap_b32_e32 v33, v205
	v_mov_b32_e32 v34, v2
	v_mov_b32_e32 v204, v2
	v_mov_b32_e32 v35, v3
	v_mov_b32_e32 v205, v3
	s_nop 1
	v_permlane32_swap_b32_e32 v34, v204
	v_permlane32_swap_b32_e32 v35, v205
	v_mov_b32_e32 v36, v4
	v_mov_b32_e32 v204, v4
	v_mov_b32_e32 v37, v5
	v_mov_b32_e32 v205, v5
	s_nop 1
	v_permlane32_swap_b32_e32 v36, v204
	v_permlane32_swap_b32_e32 v37, v205
	v_mov_b32_e32 v38, v6
	v_mov_b32_e32 v204, v6
	v_mov_b32_e32 v39, v7
	v_mov_b32_e32 v205, v7
	s_nop 1
	v_permlane32_swap_b32_e32 v38, v204
	v_permlane32_swap_b32_e32 v39, v205
	v_mov_b32_e32 v40, v8
	v_mov_b32_e32 v204, v8
	v_mov_b32_e32 v41, v9
	v_mov_b32_e32 v205, v9
	s_nop 1
	v_permlane32_swap_b32_e32 v40, v204
	v_permlane32_swap_b32_e32 v41, v205
	v_mov_b32_e32 v42, v10
	v_mov_b32_e32 v204, v10
	v_mov_b32_e32 v43, v11
	v_mov_b32_e32 v205, v11
	s_nop 1
	v_permlane32_swap_b32_e32 v42, v204
	v_permlane32_swap_b32_e32 v43, v205
	v_mov_b32_e32 v44, v12
	v_mov_b32_e32 v204, v12
	v_mov_b32_e32 v45, v13
	v_mov_b32_e32 v205, v13
	s_nop 1
	v_permlane32_swap_b32_e32 v44, v204
	v_permlane32_swap_b32_e32 v45, v205
	v_mov_b32_e32 v46, v14
	v_mov_b32_e32 v204, v14
	v_mov_b32_e32 v47, v15
	v_mov_b32_e32 v205, v15
	s_nop 1
	v_permlane32_swap_b32_e32 v46, v204
	v_permlane32_swap_b32_e32 v47, v205
	v_mov_b32_e32 v48, v16
	v_mov_b32_e32 v204, v16
	v_mov_b32_e32 v49, v17
	v_mov_b32_e32 v205, v17
	s_nop 1
	v_permlane32_swap_b32_e32 v48, v204
	v_permlane32_swap_b32_e32 v49, v205
	v_mov_b32_e32 v50, v18
	v_mov_b32_e32 v204, v18
	v_mov_b32_e32 v51, v19
	v_mov_b32_e32 v205, v19
	s_nop 1
	v_permlane32_swap_b32_e32 v50, v204
	v_permlane32_swap_b32_e32 v51, v205
	v_mov_b32_e32 v52, v20
	v_mov_b32_e32 v204, v20
	v_mov_b32_e32 v53, v21
	v_mov_b32_e32 v205, v21
	s_nop 1
	v_permlane32_swap_b32_e32 v52, v204
	v_permlane32_swap_b32_e32 v53, v205
	v_mov_b32_e32 v54, v22
	v_mov_b32_e32 v204, v22
	v_mov_b32_e32 v55, v23
	v_mov_b32_e32 v205, v23
	s_nop 1
	v_permlane32_swap_b32_e32 v54, v204
	v_permlane32_swap_b32_e32 v55, v205
	v_mov_b32_e32 v56, v24
	v_mov_b32_e32 v204, v24
	v_mov_b32_e32 v57, v25
	v_mov_b32_e32 v205, v25
	s_nop 1
	v_permlane32_swap_b32_e32 v56, v204
	v_permlane32_swap_b32_e32 v57, v205
	v_mov_b32_e32 v58, v26
	v_mov_b32_e32 v204, v26
	v_mov_b32_e32 v59, v27
	v_mov_b32_e32 v205, v27
	s_nop 1
	v_permlane32_swap_b32_e32 v58, v204
	v_permlane32_swap_b32_e32 v59, v205
	v_mov_b32_e32 v60, v28
	v_mov_b32_e32 v204, v28
	v_mov_b32_e32 v61, v29
	v_mov_b32_e32 v205, v29
	s_nop 1
	v_permlane32_swap_b32_e32 v60, v204
	v_permlane32_swap_b32_e32 v61, v205
	v_mov_b32_e32 v62, v30
	v_mov_b32_e32 v204, v30
	v_mov_b32_e32 v63, v31
	v_mov_b32_e32 v205, v31
	s_nop 1
	v_permlane32_swap_b32_e32 v62, v204
	v_permlane32_swap_b32_e32 v63, v205
	s_waitcnt lgkmcnt(14)
	ds_read_b128 v[80:83], v196 offset:0
	s_waitcnt lgkmcnt(14)
	ds_read_b128 v[84:87], v196 offset:16
	s_waitcnt lgkmcnt(14)
	ds_read_b128 v[88:91], v196 offset:32
	s_waitcnt lgkmcnt(14)
	ds_read_b128 v[92:95], v196 offset:48
	s_waitcnt lgkmcnt(14)
	ds_read_b128 v[96:99], v196 offset:64
	s_waitcnt lgkmcnt(14)
	ds_read_b128 v[100:103], v196 offset:80
	s_waitcnt lgkmcnt(14)
	ds_read_b128 v[104:107], v196 offset:96
	s_waitcnt lgkmcnt(14)
	ds_read_b128 v[108:111], v196 offset:112
	s_waitcnt lgkmcnt(14)
	ds_read_b128 v[112:115], v196 offset:272
	s_waitcnt lgkmcnt(14)
	ds_read_b128 v[116:119], v196 offset:288
	s_waitcnt lgkmcnt(14)
	ds_read_b128 v[120:123], v196 offset:304
	s_waitcnt lgkmcnt(14)
	ds_read_b128 v[124:127], v196 offset:320
	s_waitcnt lgkmcnt(14)
	ds_read_b128 v[130:133], v196 offset:336
	s_waitcnt lgkmcnt(14)
	ds_read_b128 v[134:137], v196 offset:352
	s_waitcnt lgkmcnt(14)
	ds_read_b128 v[138:141], v196 offset:368
	s_waitcnt lgkmcnt(14)
	ds_read_b128 v[142:145], v196 offset:384
	s_waitcnt lgkmcnt(12)
	v_pk_fma_f32 v[146:147], v[80:81], v[32:33], v[200:201]
	v_pk_fma_f32 v[148:149], v[82:83], v[34:35], v[200:201]
	v_pk_fma_f32 v[150:151], v[84:85], v[36:37], v[200:201]
	v_pk_fma_f32 v[152:153], v[86:87], v[38:39], v[200:201]
	v_pk_fma_f32 v[146:147], v[88:89], v[40:41], v[146:147]
	v_pk_fma_f32 v[148:149], v[90:91], v[42:43], v[148:149]
	v_pk_fma_f32 v[150:151], v[92:93], v[44:45], v[150:151]
	v_pk_fma_f32 v[152:153], v[94:95], v[46:47], v[152:153]
	s_waitcnt lgkmcnt(8)
	v_pk_fma_f32 v[146:147], v[96:97], v[48:49], v[146:147]
	v_pk_fma_f32 v[148:149], v[98:99], v[50:51], v[148:149]
	v_pk_fma_f32 v[150:151], v[100:101], v[52:53], v[150:151]
	v_pk_fma_f32 v[152:153], v[102:103], v[54:55], v[152:153]
	v_pk_fma_f32 v[146:147], v[104:105], v[56:57], v[146:147]
	v_pk_fma_f32 v[148:149], v[106:107], v[58:59], v[148:149]
	v_pk_fma_f32 v[150:151], v[108:109], v[60:61], v[150:151]
	v_pk_fma_f32 v[152:153], v[110:111], v[62:63], v[152:153]
	v_pk_add_f32 v[146:147], v[146:147], v[150:151]
	v_pk_add_f32 v[148:149], v[148:149], v[152:153]
	v_add_f32_e32 v146, v147, v146
	v_add_f32_e32 v148, v148, v149
	v_add_f32_e32 v64, v148, v146
	ds_read_b128 v[80:83], v196 offset:544
	ds_read_b128 v[84:87], v196 offset:560
	ds_read_b128 v[88:91], v196 offset:576
	ds_read_b128 v[92:95], v196 offset:592
	ds_read_b128 v[96:99], v196 offset:608
	ds_read_b128 v[100:103], v196 offset:624
	ds_read_b128 v[104:107], v196 offset:640
	s_waitcnt lgkmcnt(14)
	ds_read_b128 v[108:111], v196 offset:656
	s_waitcnt lgkmcnt(12)
	v_pk_fma_f32 v[146:147], v[112:113], v[32:33], v[200:201]
	v_pk_fma_f32 v[148:149], v[114:115], v[34:35], v[200:201]
	v_pk_fma_f32 v[150:151], v[116:117], v[36:37], v[200:201]
	v_pk_fma_f32 v[152:153], v[118:119], v[38:39], v[200:201]
	v_pk_fma_f32 v[146:147], v[120:121], v[40:41], v[146:147]
	v_pk_fma_f32 v[148:149], v[122:123], v[42:43], v[148:149]
	v_pk_fma_f32 v[150:151], v[124:125], v[44:45], v[150:151]
	v_pk_fma_f32 v[152:153], v[126:127], v[46:47], v[152:153]
	s_waitcnt lgkmcnt(8)
	v_pk_fma_f32 v[146:147], v[130:131], v[48:49], v[146:147]
	v_pk_fma_f32 v[148:149], v[132:133], v[50:51], v[148:149]
	v_pk_fma_f32 v[150:151], v[134:135], v[52:53], v[150:151]
	v_pk_fma_f32 v[152:153], v[136:137], v[54:55], v[152:153]
	v_pk_fma_f32 v[146:147], v[138:139], v[56:57], v[146:147]
	v_pk_fma_f32 v[148:149], v[140:141], v[58:59], v[148:149]
	v_pk_fma_f32 v[150:151], v[142:143], v[60:61], v[150:151]
	v_pk_fma_f32 v[152:153], v[144:145], v[62:63], v[152:153]
	v_pk_add_f32 v[146:147], v[146:147], v[150:151]
	v_pk_add_f32 v[148:149], v[148:149], v[152:153]
	v_add_f32_e32 v146, v147, v146
	v_add_f32_e32 v148, v148, v149
	v_add_f32_e32 v65, v148, v146
	ds_read_b128 v[112:115], v196 offset:816
	ds_read_b128 v[116:119], v196 offset:832
	ds_read_b128 v[120:123], v196 offset:848
	ds_read_b128 v[124:127], v196 offset:864
	ds_read_b128 v[130:133], v196 offset:880
	ds_read_b128 v[134:137], v196 offset:896
	ds_read_b128 v[138:141], v196 offset:912
	s_waitcnt lgkmcnt(14)
	ds_read_b128 v[142:145], v196 offset:928
	s_waitcnt lgkmcnt(12)
	v_pk_fma_f32 v[146:147], v[80:81], v[32:33], v[200:201]
	v_pk_fma_f32 v[148:149], v[82:83], v[34:35], v[200:201]
	v_pk_fma_f32 v[150:151], v[84:85], v[36:37], v[200:201]
	v_pk_fma_f32 v[152:153], v[86:87], v[38:39], v[200:201]
	v_pk_fma_f32 v[146:147], v[88:89], v[40:41], v[146:147]
	v_pk_fma_f32 v[148:149], v[90:91], v[42:43], v[148:149]
	v_pk_fma_f32 v[150:151], v[92:93], v[44:45], v[150:151]
	v_pk_fma_f32 v[152:153], v[94:95], v[46:47], v[152:153]
	s_waitcnt lgkmcnt(8)
	v_pk_fma_f32 v[146:147], v[96:97], v[48:49], v[146:147]
	v_pk_fma_f32 v[148:149], v[98:99], v[50:51], v[148:149]
	v_pk_fma_f32 v[150:151], v[100:101], v[52:53], v[150:151]
	v_pk_fma_f32 v[152:153], v[102:103], v[54:55], v[152:153]
	v_pk_fma_f32 v[146:147], v[104:105], v[56:57], v[146:147]
	v_pk_fma_f32 v[148:149], v[106:107], v[58:59], v[148:149]
	v_pk_fma_f32 v[150:151], v[108:109], v[60:61], v[150:151]
	v_pk_fma_f32 v[152:153], v[110:111], v[62:63], v[152:153]
	v_pk_add_f32 v[146:147], v[146:147], v[150:151]
	v_pk_add_f32 v[148:149], v[148:149], v[152:153]
	v_add_f32_e32 v146, v147, v146
	v_add_f32_e32 v148, v148, v149
	v_add_f32_e32 v66, v148, v146
	ds_read_b128 v[80:83], v196 offset:1088
	ds_read_b128 v[84:87], v196 offset:1104
	ds_read_b128 v[88:91], v196 offset:1120
	ds_read_b128 v[92:95], v196 offset:1136
	ds_read_b128 v[96:99], v196 offset:1152
	ds_read_b128 v[100:103], v196 offset:1168
	ds_read_b128 v[104:107], v196 offset:1184
	s_waitcnt lgkmcnt(14)
	ds_read_b128 v[108:111], v196 offset:1200
	s_waitcnt lgkmcnt(12)
	v_pk_fma_f32 v[146:147], v[112:113], v[32:33], v[200:201]
	v_pk_fma_f32 v[148:149], v[114:115], v[34:35], v[200:201]
	v_pk_fma_f32 v[150:151], v[116:117], v[36:37], v[200:201]
	v_pk_fma_f32 v[152:153], v[118:119], v[38:39], v[200:201]
	v_pk_fma_f32 v[146:147], v[120:121], v[40:41], v[146:147]
	v_pk_fma_f32 v[148:149], v[122:123], v[42:43], v[148:149]
	v_pk_fma_f32 v[150:151], v[124:125], v[44:45], v[150:151]
	v_pk_fma_f32 v[152:153], v[126:127], v[46:47], v[152:153]
	s_waitcnt lgkmcnt(8)
	v_pk_fma_f32 v[146:147], v[130:131], v[48:49], v[146:147]
	v_pk_fma_f32 v[148:149], v[132:133], v[50:51], v[148:149]
	v_pk_fma_f32 v[150:151], v[134:135], v[52:53], v[150:151]
	v_pk_fma_f32 v[152:153], v[136:137], v[54:55], v[152:153]
	v_pk_fma_f32 v[146:147], v[138:139], v[56:57], v[146:147]
	v_pk_fma_f32 v[148:149], v[140:141], v[58:59], v[148:149]
	v_pk_fma_f32 v[150:151], v[142:143], v[60:61], v[150:151]
	v_pk_fma_f32 v[152:153], v[144:145], v[62:63], v[152:153]
	v_pk_add_f32 v[146:147], v[146:147], v[150:151]
	v_pk_add_f32 v[148:149], v[148:149], v[152:153]
	v_add_f32_e32 v146, v147, v146
	v_add_f32_e32 v148, v148, v149
	v_add_f32_e32 v67, v148, v146
	ds_read_b128 v[112:115], v196 offset:1360
	ds_read_b128 v[116:119], v196 offset:1376
	ds_read_b128 v[120:123], v196 offset:1392
	ds_read_b128 v[124:127], v196 offset:1408
	ds_read_b128 v[130:133], v196 offset:1424
	ds_read_b128 v[134:137], v196 offset:1440
	ds_read_b128 v[138:141], v196 offset:1456
	s_waitcnt lgkmcnt(14)
	ds_read_b128 v[142:145], v196 offset:1472
	s_waitcnt lgkmcnt(12)
	v_pk_fma_f32 v[146:147], v[80:81], v[32:33], v[200:201]
	v_pk_fma_f32 v[148:149], v[82:83], v[34:35], v[200:201]
	v_pk_fma_f32 v[150:151], v[84:85], v[36:37], v[200:201]
	v_pk_fma_f32 v[152:153], v[86:87], v[38:39], v[200:201]
	v_pk_fma_f32 v[146:147], v[88:89], v[40:41], v[146:147]
	v_pk_fma_f32 v[148:149], v[90:91], v[42:43], v[148:149]
	v_pk_fma_f32 v[150:151], v[92:93], v[44:45], v[150:151]
	v_pk_fma_f32 v[152:153], v[94:95], v[46:47], v[152:153]
	s_waitcnt lgkmcnt(8)
	v_pk_fma_f32 v[146:147], v[96:97], v[48:49], v[146:147]
	v_pk_fma_f32 v[148:149], v[98:99], v[50:51], v[148:149]
	v_pk_fma_f32 v[150:151], v[100:101], v[52:53], v[150:151]
	v_pk_fma_f32 v[152:153], v[102:103], v[54:55], v[152:153]
	v_pk_fma_f32 v[146:147], v[104:105], v[56:57], v[146:147]
	v_pk_fma_f32 v[148:149], v[106:107], v[58:59], v[148:149]
	v_pk_fma_f32 v[150:151], v[108:109], v[60:61], v[150:151]
	v_pk_fma_f32 v[152:153], v[110:111], v[62:63], v[152:153]
	v_pk_add_f32 v[146:147], v[146:147], v[150:151]
	v_pk_add_f32 v[148:149], v[148:149], v[152:153]
	v_add_f32_e32 v146, v147, v146
	v_add_f32_e32 v148, v148, v149
	v_add_f32_e32 v68, v148, v146
	ds_read_b128 v[80:83], v196 offset:1632
	ds_read_b128 v[84:87], v196 offset:1648
	ds_read_b128 v[88:91], v196 offset:1664
	ds_read_b128 v[92:95], v196 offset:1680
	ds_read_b128 v[96:99], v196 offset:1696
	ds_read_b128 v[100:103], v196 offset:1712
	ds_read_b128 v[104:107], v196 offset:1728
	s_waitcnt lgkmcnt(14)
	ds_read_b128 v[108:111], v196 offset:1744
	s_waitcnt lgkmcnt(12)
	v_pk_fma_f32 v[146:147], v[112:113], v[32:33], v[200:201]
	v_pk_fma_f32 v[148:149], v[114:115], v[34:35], v[200:201]
	v_pk_fma_f32 v[150:151], v[116:117], v[36:37], v[200:201]
	v_pk_fma_f32 v[152:153], v[118:119], v[38:39], v[200:201]
	v_pk_fma_f32 v[146:147], v[120:121], v[40:41], v[146:147]
	v_pk_fma_f32 v[148:149], v[122:123], v[42:43], v[148:149]
	v_pk_fma_f32 v[150:151], v[124:125], v[44:45], v[150:151]
	v_pk_fma_f32 v[152:153], v[126:127], v[46:47], v[152:153]
	s_waitcnt lgkmcnt(8)
	v_pk_fma_f32 v[146:147], v[130:131], v[48:49], v[146:147]
	v_pk_fma_f32 v[148:149], v[132:133], v[50:51], v[148:149]
	v_pk_fma_f32 v[150:151], v[134:135], v[52:53], v[150:151]
	v_pk_fma_f32 v[152:153], v[136:137], v[54:55], v[152:153]
	v_pk_fma_f32 v[146:147], v[138:139], v[56:57], v[146:147]
	v_pk_fma_f32 v[148:149], v[140:141], v[58:59], v[148:149]
	v_pk_fma_f32 v[150:151], v[142:143], v[60:61], v[150:151]
	v_pk_fma_f32 v[152:153], v[144:145], v[62:63], v[152:153]
	v_pk_add_f32 v[146:147], v[146:147], v[150:151]
	v_pk_add_f32 v[148:149], v[148:149], v[152:153]
	v_add_f32_e32 v146, v147, v146
	v_add_f32_e32 v148, v148, v149
	v_add_f32_e32 v69, v148, v146
	ds_read_b128 v[112:115], v196 offset:1904
	ds_read_b128 v[116:119], v196 offset:1920
	ds_read_b128 v[120:123], v196 offset:1936
	ds_read_b128 v[124:127], v196 offset:1952
	ds_read_b128 v[130:133], v196 offset:1968
	ds_read_b128 v[134:137], v196 offset:1984
	ds_read_b128 v[138:141], v196 offset:2000
	s_waitcnt lgkmcnt(14)
	ds_read_b128 v[142:145], v196 offset:2016
	s_waitcnt lgkmcnt(12)
	v_pk_fma_f32 v[146:147], v[80:81], v[32:33], v[200:201]
	v_pk_fma_f32 v[148:149], v[82:83], v[34:35], v[200:201]
	v_pk_fma_f32 v[150:151], v[84:85], v[36:37], v[200:201]
	v_pk_fma_f32 v[152:153], v[86:87], v[38:39], v[200:201]
	v_pk_fma_f32 v[146:147], v[88:89], v[40:41], v[146:147]
	v_pk_fma_f32 v[148:149], v[90:91], v[42:43], v[148:149]
	v_pk_fma_f32 v[150:151], v[92:93], v[44:45], v[150:151]
	v_pk_fma_f32 v[152:153], v[94:95], v[46:47], v[152:153]
	s_waitcnt lgkmcnt(8)
	v_pk_fma_f32 v[146:147], v[96:97], v[48:49], v[146:147]
	v_pk_fma_f32 v[148:149], v[98:99], v[50:51], v[148:149]
	v_pk_fma_f32 v[150:151], v[100:101], v[52:53], v[150:151]
	v_pk_fma_f32 v[152:153], v[102:103], v[54:55], v[152:153]
	v_pk_fma_f32 v[146:147], v[104:105], v[56:57], v[146:147]
	v_pk_fma_f32 v[148:149], v[106:107], v[58:59], v[148:149]
	v_pk_fma_f32 v[150:151], v[108:109], v[60:61], v[150:151]
	v_pk_fma_f32 v[152:153], v[110:111], v[62:63], v[152:153]
	v_pk_add_f32 v[146:147], v[146:147], v[150:151]
	v_pk_add_f32 v[148:149], v[148:149], v[152:153]
	v_add_f32_e32 v146, v147, v146
	v_add_f32_e32 v148, v148, v149
	v_add_f32_e32 v70, v148, v146
	ds_read_b128 v[80:83], v196 offset:2176
	ds_read_b128 v[84:87], v196 offset:2192
	ds_read_b128 v[88:91], v196 offset:2208
	ds_read_b128 v[92:95], v196 offset:2224
	ds_read_b128 v[96:99], v196 offset:2240
	ds_read_b128 v[100:103], v196 offset:2256
	ds_read_b128 v[104:107], v196 offset:2272
	s_waitcnt lgkmcnt(14)
	ds_read_b128 v[108:111], v196 offset:2288
	s_waitcnt lgkmcnt(12)
	v_pk_fma_f32 v[146:147], v[112:113], v[32:33], v[200:201]
	v_pk_fma_f32 v[148:149], v[114:115], v[34:35], v[200:201]
	v_pk_fma_f32 v[150:151], v[116:117], v[36:37], v[200:201]
	v_pk_fma_f32 v[152:153], v[118:119], v[38:39], v[200:201]
	v_pk_fma_f32 v[146:147], v[120:121], v[40:41], v[146:147]
	v_pk_fma_f32 v[148:149], v[122:123], v[42:43], v[148:149]
	v_pk_fma_f32 v[150:151], v[124:125], v[44:45], v[150:151]
	v_pk_fma_f32 v[152:153], v[126:127], v[46:47], v[152:153]
	s_waitcnt lgkmcnt(8)
	v_pk_fma_f32 v[146:147], v[130:131], v[48:49], v[146:147]
	v_pk_fma_f32 v[148:149], v[132:133], v[50:51], v[148:149]
	v_pk_fma_f32 v[150:151], v[134:135], v[52:53], v[150:151]
	v_pk_fma_f32 v[152:153], v[136:137], v[54:55], v[152:153]
	v_pk_fma_f32 v[146:147], v[138:139], v[56:57], v[146:147]
	v_pk_fma_f32 v[148:149], v[140:141], v[58:59], v[148:149]
	v_pk_fma_f32 v[150:151], v[142:143], v[60:61], v[150:151]
	v_pk_fma_f32 v[152:153], v[144:145], v[62:63], v[152:153]
	v_pk_add_f32 v[146:147], v[146:147], v[150:151]
	v_pk_add_f32 v[148:149], v[148:149], v[152:153]
	v_add_f32_e32 v146, v147, v146
	v_add_f32_e32 v148, v148, v149
	v_add_f32_e32 v71, v148, v146
	ds_read_b128 v[112:115], v196 offset:2448
	ds_read_b128 v[116:119], v196 offset:2464
	ds_read_b128 v[120:123], v196 offset:2480
	ds_read_b128 v[124:127], v196 offset:2496
	ds_read_b128 v[130:133], v196 offset:2512
	ds_read_b128 v[134:137], v196 offset:2528
	ds_read_b128 v[138:141], v196 offset:2544
	s_waitcnt lgkmcnt(14)
	ds_read_b128 v[142:145], v196 offset:2560
	s_waitcnt lgkmcnt(12)
	v_pk_fma_f32 v[146:147], v[80:81], v[32:33], v[200:201]
	v_pk_fma_f32 v[148:149], v[82:83], v[34:35], v[200:201]
	v_pk_fma_f32 v[150:151], v[84:85], v[36:37], v[200:201]
	v_pk_fma_f32 v[152:153], v[86:87], v[38:39], v[200:201]
	v_pk_fma_f32 v[146:147], v[88:89], v[40:41], v[146:147]
	v_pk_fma_f32 v[148:149], v[90:91], v[42:43], v[148:149]
	v_pk_fma_f32 v[150:151], v[92:93], v[44:45], v[150:151]
	v_pk_fma_f32 v[152:153], v[94:95], v[46:47], v[152:153]
	s_waitcnt lgkmcnt(8)
	v_pk_fma_f32 v[146:147], v[96:97], v[48:49], v[146:147]
	v_pk_fma_f32 v[148:149], v[98:99], v[50:51], v[148:149]
	v_pk_fma_f32 v[150:151], v[100:101], v[52:53], v[150:151]
	v_pk_fma_f32 v[152:153], v[102:103], v[54:55], v[152:153]
	v_pk_fma_f32 v[146:147], v[104:105], v[56:57], v[146:147]
	v_pk_fma_f32 v[148:149], v[106:107], v[58:59], v[148:149]
	v_pk_fma_f32 v[150:151], v[108:109], v[60:61], v[150:151]
	v_pk_fma_f32 v[152:153], v[110:111], v[62:63], v[152:153]
	v_pk_add_f32 v[146:147], v[146:147], v[150:151]
	v_pk_add_f32 v[148:149], v[148:149], v[152:153]
	v_add_f32_e32 v146, v147, v146
	v_add_f32_e32 v148, v148, v149
	v_add_f32_e32 v72, v148, v146
	ds_read_b128 v[80:83], v196 offset:2720
	ds_read_b128 v[84:87], v196 offset:2736
	ds_read_b128 v[88:91], v196 offset:2752
	ds_read_b128 v[92:95], v196 offset:2768
	ds_read_b128 v[96:99], v196 offset:2784
	ds_read_b128 v[100:103], v196 offset:2800
	ds_read_b128 v[104:107], v196 offset:2816
	s_waitcnt lgkmcnt(14)
	ds_read_b128 v[108:111], v196 offset:2832
	s_waitcnt lgkmcnt(12)
	v_pk_fma_f32 v[146:147], v[112:113], v[32:33], v[200:201]
	v_pk_fma_f32 v[148:149], v[114:115], v[34:35], v[200:201]
	v_pk_fma_f32 v[150:151], v[116:117], v[36:37], v[200:201]
	v_pk_fma_f32 v[152:153], v[118:119], v[38:39], v[200:201]
	v_pk_fma_f32 v[146:147], v[120:121], v[40:41], v[146:147]
	v_pk_fma_f32 v[148:149], v[122:123], v[42:43], v[148:149]
	v_pk_fma_f32 v[150:151], v[124:125], v[44:45], v[150:151]
	v_pk_fma_f32 v[152:153], v[126:127], v[46:47], v[152:153]
	s_waitcnt lgkmcnt(8)
	v_pk_fma_f32 v[146:147], v[130:131], v[48:49], v[146:147]
	v_pk_fma_f32 v[148:149], v[132:133], v[50:51], v[148:149]
	v_pk_fma_f32 v[150:151], v[134:135], v[52:53], v[150:151]
	v_pk_fma_f32 v[152:153], v[136:137], v[54:55], v[152:153]
	v_pk_fma_f32 v[146:147], v[138:139], v[56:57], v[146:147]
	v_pk_fma_f32 v[148:149], v[140:141], v[58:59], v[148:149]
	v_pk_fma_f32 v[150:151], v[142:143], v[60:61], v[150:151]
	v_pk_fma_f32 v[152:153], v[144:145], v[62:63], v[152:153]
	v_pk_add_f32 v[146:147], v[146:147], v[150:151]
	v_pk_add_f32 v[148:149], v[148:149], v[152:153]
	v_add_f32_e32 v146, v147, v146
	v_add_f32_e32 v148, v148, v149
	v_add_f32_e32 v73, v148, v146
	ds_read_b128 v[112:115], v196 offset:2992
	ds_read_b128 v[116:119], v196 offset:3008
	ds_read_b128 v[120:123], v196 offset:3024
	ds_read_b128 v[124:127], v196 offset:3040
	ds_read_b128 v[130:133], v196 offset:3056
	ds_read_b128 v[134:137], v196 offset:3072
	ds_read_b128 v[138:141], v196 offset:3088
	s_waitcnt lgkmcnt(14)
	ds_read_b128 v[142:145], v196 offset:3104
	s_waitcnt lgkmcnt(12)
	v_pk_fma_f32 v[146:147], v[80:81], v[32:33], v[200:201]
	v_pk_fma_f32 v[148:149], v[82:83], v[34:35], v[200:201]
	v_pk_fma_f32 v[150:151], v[84:85], v[36:37], v[200:201]
	v_pk_fma_f32 v[152:153], v[86:87], v[38:39], v[200:201]
	v_pk_fma_f32 v[146:147], v[88:89], v[40:41], v[146:147]
	v_pk_fma_f32 v[148:149], v[90:91], v[42:43], v[148:149]
	v_pk_fma_f32 v[150:151], v[92:93], v[44:45], v[150:151]
	v_pk_fma_f32 v[152:153], v[94:95], v[46:47], v[152:153]
	s_waitcnt lgkmcnt(8)
	v_pk_fma_f32 v[146:147], v[96:97], v[48:49], v[146:147]
	v_pk_fma_f32 v[148:149], v[98:99], v[50:51], v[148:149]
	v_pk_fma_f32 v[150:151], v[100:101], v[52:53], v[150:151]
	v_pk_fma_f32 v[152:153], v[102:103], v[54:55], v[152:153]
	v_pk_fma_f32 v[146:147], v[104:105], v[56:57], v[146:147]
	v_pk_fma_f32 v[148:149], v[106:107], v[58:59], v[148:149]
	v_pk_fma_f32 v[150:151], v[108:109], v[60:61], v[150:151]
	v_pk_fma_f32 v[152:153], v[110:111], v[62:63], v[152:153]
	v_pk_add_f32 v[146:147], v[146:147], v[150:151]
	v_pk_add_f32 v[148:149], v[148:149], v[152:153]
	v_add_f32_e32 v146, v147, v146
	v_add_f32_e32 v148, v148, v149
	v_add_f32_e32 v74, v148, v146
	ds_read_b128 v[80:83], v196 offset:3264
	ds_read_b128 v[84:87], v196 offset:3280
	ds_read_b128 v[88:91], v196 offset:3296
	ds_read_b128 v[92:95], v196 offset:3312
	ds_read_b128 v[96:99], v196 offset:3328
	ds_read_b128 v[100:103], v196 offset:3344
	ds_read_b128 v[104:107], v196 offset:3360
	s_waitcnt lgkmcnt(14)
	ds_read_b128 v[108:111], v196 offset:3376
	s_waitcnt lgkmcnt(12)
	v_pk_fma_f32 v[146:147], v[112:113], v[32:33], v[200:201]
	v_pk_fma_f32 v[148:149], v[114:115], v[34:35], v[200:201]
	v_pk_fma_f32 v[150:151], v[116:117], v[36:37], v[200:201]
	v_pk_fma_f32 v[152:153], v[118:119], v[38:39], v[200:201]
	v_pk_fma_f32 v[146:147], v[120:121], v[40:41], v[146:147]
	v_pk_fma_f32 v[148:149], v[122:123], v[42:43], v[148:149]
	v_pk_fma_f32 v[150:151], v[124:125], v[44:45], v[150:151]
	v_pk_fma_f32 v[152:153], v[126:127], v[46:47], v[152:153]
	s_waitcnt lgkmcnt(8)
	v_pk_fma_f32 v[146:147], v[130:131], v[48:49], v[146:147]
	v_pk_fma_f32 v[148:149], v[132:133], v[50:51], v[148:149]
	v_pk_fma_f32 v[150:151], v[134:135], v[52:53], v[150:151]
	v_pk_fma_f32 v[152:153], v[136:137], v[54:55], v[152:153]
	v_pk_fma_f32 v[146:147], v[138:139], v[56:57], v[146:147]
	v_pk_fma_f32 v[148:149], v[140:141], v[58:59], v[148:149]
	v_pk_fma_f32 v[150:151], v[142:143], v[60:61], v[150:151]
	v_pk_fma_f32 v[152:153], v[144:145], v[62:63], v[152:153]
	v_pk_add_f32 v[146:147], v[146:147], v[150:151]
	v_pk_add_f32 v[148:149], v[148:149], v[152:153]
	v_add_f32_e32 v146, v147, v146
	v_add_f32_e32 v148, v148, v149
	v_add_f32_e32 v75, v148, v146
	ds_read_b128 v[112:115], v196 offset:3536
	ds_read_b128 v[116:119], v196 offset:3552
	ds_read_b128 v[120:123], v196 offset:3568
	ds_read_b128 v[124:127], v196 offset:3584
	ds_read_b128 v[130:133], v196 offset:3600
	ds_read_b128 v[134:137], v196 offset:3616
	ds_read_b128 v[138:141], v196 offset:3632
	s_waitcnt lgkmcnt(14)
	ds_read_b128 v[142:145], v196 offset:3648
	s_waitcnt lgkmcnt(12)
	v_pk_fma_f32 v[146:147], v[80:81], v[32:33], v[200:201]
	v_pk_fma_f32 v[148:149], v[82:83], v[34:35], v[200:201]
	v_pk_fma_f32 v[150:151], v[84:85], v[36:37], v[200:201]
	v_pk_fma_f32 v[152:153], v[86:87], v[38:39], v[200:201]
	v_pk_fma_f32 v[146:147], v[88:89], v[40:41], v[146:147]
	v_pk_fma_f32 v[148:149], v[90:91], v[42:43], v[148:149]
	v_pk_fma_f32 v[150:151], v[92:93], v[44:45], v[150:151]
	v_pk_fma_f32 v[152:153], v[94:95], v[46:47], v[152:153]
	s_waitcnt lgkmcnt(8)
	v_pk_fma_f32 v[146:147], v[96:97], v[48:49], v[146:147]
	v_pk_fma_f32 v[148:149], v[98:99], v[50:51], v[148:149]
	v_pk_fma_f32 v[150:151], v[100:101], v[52:53], v[150:151]
	v_pk_fma_f32 v[152:153], v[102:103], v[54:55], v[152:153]
	v_pk_fma_f32 v[146:147], v[104:105], v[56:57], v[146:147]
	v_pk_fma_f32 v[148:149], v[106:107], v[58:59], v[148:149]
	v_pk_fma_f32 v[150:151], v[108:109], v[60:61], v[150:151]
	v_pk_fma_f32 v[152:153], v[110:111], v[62:63], v[152:153]
	v_pk_add_f32 v[146:147], v[146:147], v[150:151]
	v_pk_add_f32 v[148:149], v[148:149], v[152:153]
	v_add_f32_e32 v146, v147, v146
	v_add_f32_e32 v148, v148, v149
	v_add_f32_e32 v76, v148, v146
	ds_read_b128 v[80:83], v196 offset:3808
	ds_read_b128 v[84:87], v196 offset:3824
	ds_read_b128 v[88:91], v196 offset:3840
	ds_read_b128 v[92:95], v196 offset:3856
	ds_read_b128 v[96:99], v196 offset:3872
	ds_read_b128 v[100:103], v196 offset:3888
	ds_read_b128 v[104:107], v196 offset:3904
	s_waitcnt lgkmcnt(14)
	ds_read_b128 v[108:111], v196 offset:3920
	s_waitcnt lgkmcnt(12)
	v_pk_fma_f32 v[146:147], v[112:113], v[32:33], v[200:201]
	v_pk_fma_f32 v[148:149], v[114:115], v[34:35], v[200:201]
	v_pk_fma_f32 v[150:151], v[116:117], v[36:37], v[200:201]
	v_pk_fma_f32 v[152:153], v[118:119], v[38:39], v[200:201]
	v_pk_fma_f32 v[146:147], v[120:121], v[40:41], v[146:147]
	v_pk_fma_f32 v[148:149], v[122:123], v[42:43], v[148:149]
	v_pk_fma_f32 v[150:151], v[124:125], v[44:45], v[150:151]
	v_pk_fma_f32 v[152:153], v[126:127], v[46:47], v[152:153]
	s_waitcnt lgkmcnt(8)
	v_pk_fma_f32 v[146:147], v[130:131], v[48:49], v[146:147]
	v_pk_fma_f32 v[148:149], v[132:133], v[50:51], v[148:149]
	v_pk_fma_f32 v[150:151], v[134:135], v[52:53], v[150:151]
	v_pk_fma_f32 v[152:153], v[136:137], v[54:55], v[152:153]
	v_pk_fma_f32 v[146:147], v[138:139], v[56:57], v[146:147]
	v_pk_fma_f32 v[148:149], v[140:141], v[58:59], v[148:149]
	v_pk_fma_f32 v[150:151], v[142:143], v[60:61], v[150:151]
	v_pk_fma_f32 v[152:153], v[144:145], v[62:63], v[152:153]
	v_pk_add_f32 v[146:147], v[146:147], v[150:151]
	v_pk_add_f32 v[148:149], v[148:149], v[152:153]
	v_add_f32_e32 v146, v147, v146
	v_add_f32_e32 v148, v148, v149
	v_add_f32_e32 v77, v148, v146
	ds_read_b128 v[112:115], v196 offset:4080
	ds_read_b128 v[116:119], v196 offset:4096
	ds_read_b128 v[120:123], v196 offset:4112
	ds_read_b128 v[124:127], v196 offset:4128
	ds_read_b128 v[130:133], v196 offset:4144
	ds_read_b128 v[134:137], v196 offset:4160
	ds_read_b128 v[138:141], v196 offset:4176
	s_waitcnt lgkmcnt(14)
	ds_read_b128 v[142:145], v196 offset:4192
	s_waitcnt lgkmcnt(12)
	v_pk_fma_f32 v[146:147], v[80:81], v[32:33], v[200:201]
	v_pk_fma_f32 v[148:149], v[82:83], v[34:35], v[200:201]
	v_pk_fma_f32 v[150:151], v[84:85], v[36:37], v[200:201]
	v_pk_fma_f32 v[152:153], v[86:87], v[38:39], v[200:201]
	v_pk_fma_f32 v[146:147], v[88:89], v[40:41], v[146:147]
	v_pk_fma_f32 v[148:149], v[90:91], v[42:43], v[148:149]
	v_pk_fma_f32 v[150:151], v[92:93], v[44:45], v[150:151]
	v_pk_fma_f32 v[152:153], v[94:95], v[46:47], v[152:153]
	s_waitcnt lgkmcnt(8)
	v_pk_fma_f32 v[146:147], v[96:97], v[48:49], v[146:147]
	v_pk_fma_f32 v[148:149], v[98:99], v[50:51], v[148:149]
	v_pk_fma_f32 v[150:151], v[100:101], v[52:53], v[150:151]
	v_pk_fma_f32 v[152:153], v[102:103], v[54:55], v[152:153]
	v_pk_fma_f32 v[146:147], v[104:105], v[56:57], v[146:147]
	v_pk_fma_f32 v[148:149], v[106:107], v[58:59], v[148:149]
	v_pk_fma_f32 v[150:151], v[108:109], v[60:61], v[150:151]
	v_pk_fma_f32 v[152:153], v[110:111], v[62:63], v[152:153]
	v_pk_add_f32 v[146:147], v[146:147], v[150:151]
	v_pk_add_f32 v[148:149], v[148:149], v[152:153]
	v_add_f32_e32 v146, v147, v146
	v_add_f32_e32 v148, v148, v149
	v_add_f32_e32 v78, v148, v146
	s_waitcnt lgkmcnt(4)
	v_pk_fma_f32 v[146:147], v[112:113], v[32:33], v[200:201]
	v_pk_fma_f32 v[148:149], v[114:115], v[34:35], v[200:201]
	v_pk_fma_f32 v[150:151], v[116:117], v[36:37], v[200:201]
	v_pk_fma_f32 v[152:153], v[118:119], v[38:39], v[200:201]
	v_pk_fma_f32 v[146:147], v[120:121], v[40:41], v[146:147]
	v_pk_fma_f32 v[148:149], v[122:123], v[42:43], v[148:149]
	v_pk_fma_f32 v[150:151], v[124:125], v[44:45], v[150:151]
	v_pk_fma_f32 v[152:153], v[126:127], v[46:47], v[152:153]
	s_waitcnt lgkmcnt(0)
	v_pk_fma_f32 v[146:147], v[130:131], v[48:49], v[146:147]
	v_pk_fma_f32 v[148:149], v[132:133], v[50:51], v[148:149]
	v_pk_fma_f32 v[150:151], v[134:135], v[52:53], v[150:151]
	v_pk_fma_f32 v[152:153], v[136:137], v[54:55], v[152:153]
	v_pk_fma_f32 v[146:147], v[138:139], v[56:57], v[146:147]
	v_pk_fma_f32 v[148:149], v[140:141], v[58:59], v[148:149]
	v_pk_fma_f32 v[150:151], v[142:143], v[60:61], v[150:151]
	v_pk_fma_f32 v[152:153], v[144:145], v[62:63], v[152:153]
	v_pk_add_f32 v[146:147], v[146:147], v[150:151]
	v_pk_add_f32 v[148:149], v[148:149], v[152:153]
	v_add_f32_e32 v146, v147, v146
	v_add_f32_e32 v148, v148, v149
	v_add_f32_e32 v79, v148, v146
	v_mov_b32_e32 v154, v64
	v_mov_b32_e32 v155, v65
	s_nop 1
	v_permlane32_swap_b32_e32 v64, v154
	v_permlane32_swap_b32_e32 v65, v155
	v_mov_b32_e32 v156, v66
	v_mov_b32_e32 v157, v67
	s_nop 1
	v_permlane32_swap_b32_e32 v66, v156
	v_permlane32_swap_b32_e32 v67, v157
	v_mov_b32_e32 v158, v68
	v_mov_b32_e32 v159, v69
	s_nop 1
	v_permlane32_swap_b32_e32 v68, v158
	v_permlane32_swap_b32_e32 v69, v159
	v_mov_b32_e32 v160, v70
	v_mov_b32_e32 v161, v71
	s_nop 1
	v_permlane32_swap_b32_e32 v70, v160
	v_permlane32_swap_b32_e32 v71, v161
	v_mov_b32_e32 v162, v72
	v_mov_b32_e32 v163, v73
	s_nop 1
	v_permlane32_swap_b32_e32 v72, v162
	v_permlane32_swap_b32_e32 v73, v163
	v_mov_b32_e32 v164, v74
	v_mov_b32_e32 v165, v75
	s_nop 1
	v_permlane32_swap_b32_e32 v74, v164
	v_permlane32_swap_b32_e32 v75, v165
	v_mov_b32_e32 v166, v76
	v_mov_b32_e32 v167, v77
	s_nop 1
	v_permlane32_swap_b32_e32 v76, v166
	v_permlane32_swap_b32_e32 v77, v167
	v_mov_b32_e32 v168, v78
	v_mov_b32_e32 v169, v79
	s_nop 1
	v_permlane32_swap_b32_e32 v78, v168
	v_permlane32_swap_b32_e32 v79, v169
	ds_read_b128 v[80:83], v197 offset:0
	ds_read_b128 v[84:87], v197 offset:16
	ds_read_b128 v[88:91], v197 offset:32
	ds_read_b128 v[92:95], v197 offset:48
	ds_read_b128 v[96:99], v197 offset:64
	ds_read_b128 v[100:103], v197 offset:80
	ds_read_b128 v[104:107], v197 offset:96
	ds_read_b128 v[108:111], v197 offset:112
	ds_read_b128 v[112:115], v197 offset:128
	ds_read_b128 v[116:119], v197 offset:144
	ds_read_b128 v[120:123], v197 offset:160
	ds_read_b128 v[124:127], v197 offset:176
	ds_read_b128 v[130:133], v197 offset:192
	ds_read_b128 v[134:137], v197 offset:208
	ds_read_b128 v[138:141], v197 offset:224
	s_waitcnt lgkmcnt(14)
	ds_read_b128 v[142:145], v197 offset:240
	s_waitcnt lgkmcnt(12)
	v_pk_fma_f32 v[146:147], v[80:81], v[64:65], v[200:201] neg_lo:[1,0,0] neg_hi:[1,0,0]
	v_pk_fma_f32 v[148:149], v[82:83], v[66:67], v[200:201] neg_lo:[1,0,0] neg_hi:[1,0,0]
	v_pk_fma_f32 v[150:151], v[84:85], v[68:69], v[200:201] neg_lo:[1,0,0] neg_hi:[1,0,0]
	v_pk_fma_f32 v[152:153], v[86:87], v[70:71], v[200:201] neg_lo:[1,0,0] neg_hi:[1,0,0]
	v_pk_fma_f32 v[146:147], v[88:89], v[72:73], v[146:147] neg_lo:[1,0,0] neg_hi:[1,0,0]
	v_pk_fma_f32 v[148:149], v[90:91], v[74:75], v[148:149] neg_lo:[1,0,0] neg_hi:[1,0,0]
	v_pk_fma_f32 v[150:151], v[92:93], v[76:77], v[150:151] neg_lo:[1,0,0] neg_hi:[1,0,0]
	v_pk_fma_f32 v[152:153], v[94:95], v[78:79], v[152:153] neg_lo:[1,0,0] neg_hi:[1,0,0]
	s_waitcnt lgkmcnt(8)
	v_pk_fma_f32 v[146:147], v[96:97], v[154:155], v[146:147] neg_lo:[1,0,0] neg_hi:[1,0,0]
	v_pk_fma_f32 v[148:149], v[98:99], v[156:157], v[148:149] neg_lo:[1,0,0] neg_hi:[1,0,0]
	v_pk_fma_f32 v[150:151], v[100:101], v[158:159], v[150:151] neg_lo:[1,0,0] neg_hi:[1,0,0]
	v_pk_fma_f32 v[152:153], v[102:103], v[160:161], v[152:153] neg_lo:[1,0,0] neg_hi:[1,0,0]
	v_pk_fma_f32 v[146:147], v[104:105], v[162:163], v[146:147] neg_lo:[1,0,0] neg_hi:[1,0,0]
	v_pk_fma_f32 v[148:149], v[106:107], v[164:165], v[148:149] neg_lo:[1,0,0] neg_hi:[1,0,0]
	v_pk_fma_f32 v[150:151], v[108:109], v[166:167], v[150:151] neg_lo:[1,0,0] neg_hi:[1,0,0]
	v_pk_fma_f32 v[152:153], v[110:111], v[168:169], v[152:153] neg_lo:[1,0,0] neg_hi:[1,0,0]
	v_pk_add_f32 v[146:147], v[146:147], v[150:151]
	v_pk_add_f32 v[148:149], v[148:149], v[152:153]
	v_add_f32_e32 v146, v147, v146
	v_add_f32_e32 v148, v148, v149
	v_add_f32_e32 v170, v148, v146
	ds_read_b128 v[80:83], v197 offset:256
	ds_read_b128 v[84:87], v197 offset:272
	ds_read_b128 v[88:91], v197 offset:288
	ds_read_b128 v[92:95], v197 offset:304
	ds_read_b128 v[96:99], v197 offset:320
	ds_read_b128 v[100:103], v197 offset:336
	ds_read_b128 v[104:107], v197 offset:352
	s_waitcnt lgkmcnt(14)
	ds_read_b128 v[108:111], v197 offset:368
	s_waitcnt lgkmcnt(12)
	v_pk_fma_f32 v[146:147], v[112:113], v[64:65], v[200:201] neg_lo:[1,0,0] neg_hi:[1,0,0]
	v_pk_fma_f32 v[148:149], v[114:115], v[66:67], v[200:201] neg_lo:[1,0,0] neg_hi:[1,0,0]
	v_pk_fma_f32 v[150:151], v[116:117], v[68:69], v[200:201] neg_lo:[1,0,0] neg_hi:[1,0,0]
	v_pk_fma_f32 v[152:153], v[118:119], v[70:71], v[200:201] neg_lo:[1,0,0] neg_hi:[1,0,0]
	v_pk_fma_f32 v[146:147], v[120:121], v[72:73], v[146:147] neg_lo:[1,0,0] neg_hi:[1,0,0]
	v_pk_fma_f32 v[148:149], v[122:123], v[74:75], v[148:149] neg_lo:[1,0,0] neg_hi:[1,0,0]
	v_pk_fma_f32 v[150:151], v[124:125], v[76:77], v[150:151] neg_lo:[1,0,0] neg_hi:[1,0,0]
	v_pk_fma_f32 v[152:153], v[126:127], v[78:79], v[152:153] neg_lo:[1,0,0] neg_hi:[1,0,0]
	s_waitcnt lgkmcnt(8)
	v_pk_fma_f32 v[146:147], v[130:131], v[154:155], v[146:147] neg_lo:[1,0,0] neg_hi:[1,0,0]
	v_pk_fma_f32 v[148:149], v[132:133], v[156:157], v[148:149] neg_lo:[1,0,0] neg_hi:[1,0,0]
	v_pk_fma_f32 v[150:151], v[134:135], v[158:159], v[150:151] neg_lo:[1,0,0] neg_hi:[1,0,0]
	v_pk_fma_f32 v[152:153], v[136:137], v[160:161], v[152:153] neg_lo:[1,0,0] neg_hi:[1,0,0]
	v_pk_fma_f32 v[146:147], v[138:139], v[162:163], v[146:147] neg_lo:[1,0,0] neg_hi:[1,0,0]
	v_pk_fma_f32 v[148:149], v[140:141], v[164:165], v[148:149] neg_lo:[1,0,0] neg_hi:[1,0,0]
	v_pk_fma_f32 v[150:151], v[142:143], v[166:167], v[150:151] neg_lo:[1,0,0] neg_hi:[1,0,0]
	v_pk_fma_f32 v[152:153], v[144:145], v[168:169], v[152:153] neg_lo:[1,0,0] neg_hi:[1,0,0]
	v_pk_add_f32 v[146:147], v[146:147], v[150:151]
	v_pk_add_f32 v[148:149], v[148:149], v[152:153]
	v_add_f32_e32 v146, v147, v146
	v_add_f32_e32 v148, v148, v149
	v_add_f32_e32 v171, v148, v146
	ds_read_b128 v[112:115], v197 offset:384
	ds_read_b128 v[116:119], v197 offset:400
	ds_read_b128 v[120:123], v197 offset:416
	ds_read_b128 v[124:127], v197 offset:432
	ds_read_b128 v[130:133], v197 offset:448
	ds_read_b128 v[134:137], v197 offset:464
	ds_read_b128 v[138:141], v197 offset:480
	s_waitcnt lgkmcnt(14)
	ds_read_b128 v[142:145], v197 offset:496
	s_waitcnt lgkmcnt(12)
	v_pk_fma_f32 v[146:147], v[80:81], v[64:65], v[200:201] neg_lo:[1,0,0] neg_hi:[1,0,0]
	v_pk_fma_f32 v[148:149], v[82:83], v[66:67], v[200:201] neg_lo:[1,0,0] neg_hi:[1,0,0]
	v_pk_fma_f32 v[150:151], v[84:85], v[68:69], v[200:201] neg_lo:[1,0,0] neg_hi:[1,0,0]
	v_pk_fma_f32 v[152:153], v[86:87], v[70:71], v[200:201] neg_lo:[1,0,0] neg_hi:[1,0,0]
	v_pk_fma_f32 v[146:147], v[88:89], v[72:73], v[146:147] neg_lo:[1,0,0] neg_hi:[1,0,0]
	v_pk_fma_f32 v[148:149], v[90:91], v[74:75], v[148:149] neg_lo:[1,0,0] neg_hi:[1,0,0]
	v_pk_fma_f32 v[150:151], v[92:93], v[76:77], v[150:151] neg_lo:[1,0,0] neg_hi:[1,0,0]
	v_pk_fma_f32 v[152:153], v[94:95], v[78:79], v[152:153] neg_lo:[1,0,0] neg_hi:[1,0,0]
	s_waitcnt lgkmcnt(8)
	v_pk_fma_f32 v[146:147], v[96:97], v[154:155], v[146:147] neg_lo:[1,0,0] neg_hi:[1,0,0]
	v_pk_fma_f32 v[148:149], v[98:99], v[156:157], v[148:149] neg_lo:[1,0,0] neg_hi:[1,0,0]
	v_pk_fma_f32 v[150:151], v[100:101], v[158:159], v[150:151] neg_lo:[1,0,0] neg_hi:[1,0,0]
	v_pk_fma_f32 v[152:153], v[102:103], v[160:161], v[152:153] neg_lo:[1,0,0] neg_hi:[1,0,0]
	v_pk_fma_f32 v[146:147], v[104:105], v[162:163], v[146:147] neg_lo:[1,0,0] neg_hi:[1,0,0]
	v_pk_fma_f32 v[148:149], v[106:107], v[164:165], v[148:149] neg_lo:[1,0,0] neg_hi:[1,0,0]
	v_pk_fma_f32 v[150:151], v[108:109], v[166:167], v[150:151] neg_lo:[1,0,0] neg_hi:[1,0,0]
	v_pk_fma_f32 v[152:153], v[110:111], v[168:169], v[152:153] neg_lo:[1,0,0] neg_hi:[1,0,0]
	v_pk_add_f32 v[146:147], v[146:147], v[150:151]
	v_pk_add_f32 v[148:149], v[148:149], v[152:153]
	v_add_f32_e32 v146, v147, v146
	v_add_f32_e32 v148, v148, v149
	v_add_f32_e32 v172, v148, v146
	ds_read_b128 v[80:83], v197 offset:512
	ds_read_b128 v[84:87], v197 offset:528
	ds_read_b128 v[88:91], v197 offset:544
	ds_read_b128 v[92:95], v197 offset:560
	ds_read_b128 v[96:99], v197 offset:576
	ds_read_b128 v[100:103], v197 offset:592
	ds_read_b128 v[104:107], v197 offset:608
	s_waitcnt lgkmcnt(14)
	ds_read_b128 v[108:111], v197 offset:624
	s_waitcnt lgkmcnt(12)
	v_pk_fma_f32 v[146:147], v[112:113], v[64:65], v[200:201] neg_lo:[1,0,0] neg_hi:[1,0,0]
	v_pk_fma_f32 v[148:149], v[114:115], v[66:67], v[200:201] neg_lo:[1,0,0] neg_hi:[1,0,0]
	v_pk_fma_f32 v[150:151], v[116:117], v[68:69], v[200:201] neg_lo:[1,0,0] neg_hi:[1,0,0]
	v_pk_fma_f32 v[152:153], v[118:119], v[70:71], v[200:201] neg_lo:[1,0,0] neg_hi:[1,0,0]
	v_pk_fma_f32 v[146:147], v[120:121], v[72:73], v[146:147] neg_lo:[1,0,0] neg_hi:[1,0,0]
	v_pk_fma_f32 v[148:149], v[122:123], v[74:75], v[148:149] neg_lo:[1,0,0] neg_hi:[1,0,0]
	v_pk_fma_f32 v[150:151], v[124:125], v[76:77], v[150:151] neg_lo:[1,0,0] neg_hi:[1,0,0]
	v_pk_fma_f32 v[152:153], v[126:127], v[78:79], v[152:153] neg_lo:[1,0,0] neg_hi:[1,0,0]
	s_waitcnt lgkmcnt(8)
	v_pk_fma_f32 v[146:147], v[130:131], v[154:155], v[146:147] neg_lo:[1,0,0] neg_hi:[1,0,0]
	v_pk_fma_f32 v[148:149], v[132:133], v[156:157], v[148:149] neg_lo:[1,0,0] neg_hi:[1,0,0]
	v_pk_fma_f32 v[150:151], v[134:135], v[158:159], v[150:151] neg_lo:[1,0,0] neg_hi:[1,0,0]
	v_pk_fma_f32 v[152:153], v[136:137], v[160:161], v[152:153] neg_lo:[1,0,0] neg_hi:[1,0,0]
	v_pk_fma_f32 v[146:147], v[138:139], v[162:163], v[146:147] neg_lo:[1,0,0] neg_hi:[1,0,0]
	v_pk_fma_f32 v[148:149], v[140:141], v[164:165], v[148:149] neg_lo:[1,0,0] neg_hi:[1,0,0]
	v_pk_fma_f32 v[150:151], v[142:143], v[166:167], v[150:151] neg_lo:[1,0,0] neg_hi:[1,0,0]
	v_pk_fma_f32 v[152:153], v[144:145], v[168:169], v[152:153] neg_lo:[1,0,0] neg_hi:[1,0,0]
	v_pk_add_f32 v[146:147], v[146:147], v[150:151]
	v_pk_add_f32 v[148:149], v[148:149], v[152:153]
	v_add_f32_e32 v146, v147, v146
	v_add_f32_e32 v148, v148, v149
	v_add_f32_e32 v173, v148, v146
	ds_read_b128 v[112:115], v197 offset:640
	ds_read_b128 v[116:119], v197 offset:656
	ds_read_b128 v[120:123], v197 offset:672
	ds_read_b128 v[124:127], v197 offset:688
	ds_read_b128 v[130:133], v197 offset:704
	ds_read_b128 v[134:137], v197 offset:720
	ds_read_b128 v[138:141], v197 offset:736
	s_waitcnt lgkmcnt(14)
	ds_read_b128 v[142:145], v197 offset:752
	s_waitcnt lgkmcnt(12)
	v_pk_fma_f32 v[146:147], v[80:81], v[64:65], v[200:201] neg_lo:[1,0,0] neg_hi:[1,0,0]
	v_pk_fma_f32 v[148:149], v[82:83], v[66:67], v[200:201] neg_lo:[1,0,0] neg_hi:[1,0,0]
	v_pk_fma_f32 v[150:151], v[84:85], v[68:69], v[200:201] neg_lo:[1,0,0] neg_hi:[1,0,0]
	v_pk_fma_f32 v[152:153], v[86:87], v[70:71], v[200:201] neg_lo:[1,0,0] neg_hi:[1,0,0]
	v_pk_fma_f32 v[146:147], v[88:89], v[72:73], v[146:147] neg_lo:[1,0,0] neg_hi:[1,0,0]
	v_pk_fma_f32 v[148:149], v[90:91], v[74:75], v[148:149] neg_lo:[1,0,0] neg_hi:[1,0,0]
	v_pk_fma_f32 v[150:151], v[92:93], v[76:77], v[150:151] neg_lo:[1,0,0] neg_hi:[1,0,0]
	v_pk_fma_f32 v[152:153], v[94:95], v[78:79], v[152:153] neg_lo:[1,0,0] neg_hi:[1,0,0]
	s_waitcnt lgkmcnt(8)
	v_pk_fma_f32 v[146:147], v[96:97], v[154:155], v[146:147] neg_lo:[1,0,0] neg_hi:[1,0,0]
	v_pk_fma_f32 v[148:149], v[98:99], v[156:157], v[148:149] neg_lo:[1,0,0] neg_hi:[1,0,0]
	v_pk_fma_f32 v[150:151], v[100:101], v[158:159], v[150:151] neg_lo:[1,0,0] neg_hi:[1,0,0]
	v_pk_fma_f32 v[152:153], v[102:103], v[160:161], v[152:153] neg_lo:[1,0,0] neg_hi:[1,0,0]
	v_pk_fma_f32 v[146:147], v[104:105], v[162:163], v[146:147] neg_lo:[1,0,0] neg_hi:[1,0,0]
	v_pk_fma_f32 v[148:149], v[106:107], v[164:165], v[148:149] neg_lo:[1,0,0] neg_hi:[1,0,0]
	v_pk_fma_f32 v[150:151], v[108:109], v[166:167], v[150:151] neg_lo:[1,0,0] neg_hi:[1,0,0]
	v_pk_fma_f32 v[152:153], v[110:111], v[168:169], v[152:153] neg_lo:[1,0,0] neg_hi:[1,0,0]
	v_pk_add_f32 v[146:147], v[146:147], v[150:151]
	v_pk_add_f32 v[148:149], v[148:149], v[152:153]
	v_add_f32_e32 v146, v147, v146
	v_add_f32_e32 v148, v148, v149
	v_add_f32_e32 v174, v148, v146
	ds_read_b128 v[80:83], v197 offset:768
	ds_read_b128 v[84:87], v197 offset:784
	ds_read_b128 v[88:91], v197 offset:800
	ds_read_b128 v[92:95], v197 offset:816
	ds_read_b128 v[96:99], v197 offset:832
	ds_read_b128 v[100:103], v197 offset:848
	ds_read_b128 v[104:107], v197 offset:864
	s_waitcnt lgkmcnt(14)
	ds_read_b128 v[108:111], v197 offset:880
	s_waitcnt lgkmcnt(12)
	v_pk_fma_f32 v[146:147], v[112:113], v[64:65], v[200:201] neg_lo:[1,0,0] neg_hi:[1,0,0]
	v_pk_fma_f32 v[148:149], v[114:115], v[66:67], v[200:201] neg_lo:[1,0,0] neg_hi:[1,0,0]
	v_pk_fma_f32 v[150:151], v[116:117], v[68:69], v[200:201] neg_lo:[1,0,0] neg_hi:[1,0,0]
	v_pk_fma_f32 v[152:153], v[118:119], v[70:71], v[200:201] neg_lo:[1,0,0] neg_hi:[1,0,0]
	v_pk_fma_f32 v[146:147], v[120:121], v[72:73], v[146:147] neg_lo:[1,0,0] neg_hi:[1,0,0]
	v_pk_fma_f32 v[148:149], v[122:123], v[74:75], v[148:149] neg_lo:[1,0,0] neg_hi:[1,0,0]
	v_pk_fma_f32 v[150:151], v[124:125], v[76:77], v[150:151] neg_lo:[1,0,0] neg_hi:[1,0,0]
	v_pk_fma_f32 v[152:153], v[126:127], v[78:79], v[152:153] neg_lo:[1,0,0] neg_hi:[1,0,0]
	s_waitcnt lgkmcnt(8)
	v_pk_fma_f32 v[146:147], v[130:131], v[154:155], v[146:147] neg_lo:[1,0,0] neg_hi:[1,0,0]
	v_pk_fma_f32 v[148:149], v[132:133], v[156:157], v[148:149] neg_lo:[1,0,0] neg_hi:[1,0,0]
	v_pk_fma_f32 v[150:151], v[134:135], v[158:159], v[150:151] neg_lo:[1,0,0] neg_hi:[1,0,0]
	v_pk_fma_f32 v[152:153], v[136:137], v[160:161], v[152:153] neg_lo:[1,0,0] neg_hi:[1,0,0]
	v_pk_fma_f32 v[146:147], v[138:139], v[162:163], v[146:147] neg_lo:[1,0,0] neg_hi:[1,0,0]
	v_pk_fma_f32 v[148:149], v[140:141], v[164:165], v[148:149] neg_lo:[1,0,0] neg_hi:[1,0,0]
	v_pk_fma_f32 v[150:151], v[142:143], v[166:167], v[150:151] neg_lo:[1,0,0] neg_hi:[1,0,0]
	v_pk_fma_f32 v[152:153], v[144:145], v[168:169], v[152:153] neg_lo:[1,0,0] neg_hi:[1,0,0]
	v_pk_add_f32 v[146:147], v[146:147], v[150:151]
	v_pk_add_f32 v[148:149], v[148:149], v[152:153]
	v_add_f32_e32 v146, v147, v146
	v_add_f32_e32 v148, v148, v149
	v_add_f32_e32 v175, v148, v146
	ds_read_b128 v[112:115], v197 offset:896
	ds_read_b128 v[116:119], v197 offset:912
	ds_read_b128 v[120:123], v197 offset:928
	ds_read_b128 v[124:127], v197 offset:944
	ds_read_b128 v[130:133], v197 offset:960
	ds_read_b128 v[134:137], v197 offset:976
	ds_read_b128 v[138:141], v197 offset:992
	s_waitcnt lgkmcnt(14)
	ds_read_b128 v[142:145], v197 offset:1008
	s_waitcnt lgkmcnt(12)
	v_pk_fma_f32 v[146:147], v[80:81], v[64:65], v[200:201] neg_lo:[1,0,0] neg_hi:[1,0,0]
	v_pk_fma_f32 v[148:149], v[82:83], v[66:67], v[200:201] neg_lo:[1,0,0] neg_hi:[1,0,0]
	v_pk_fma_f32 v[150:151], v[84:85], v[68:69], v[200:201] neg_lo:[1,0,0] neg_hi:[1,0,0]
	v_pk_fma_f32 v[152:153], v[86:87], v[70:71], v[200:201] neg_lo:[1,0,0] neg_hi:[1,0,0]
	v_pk_fma_f32 v[146:147], v[88:89], v[72:73], v[146:147] neg_lo:[1,0,0] neg_hi:[1,0,0]
	v_pk_fma_f32 v[148:149], v[90:91], v[74:75], v[148:149] neg_lo:[1,0,0] neg_hi:[1,0,0]
	v_pk_fma_f32 v[150:151], v[92:93], v[76:77], v[150:151] neg_lo:[1,0,0] neg_hi:[1,0,0]
	v_pk_fma_f32 v[152:153], v[94:95], v[78:79], v[152:153] neg_lo:[1,0,0] neg_hi:[1,0,0]
	s_waitcnt lgkmcnt(8)
	v_pk_fma_f32 v[146:147], v[96:97], v[154:155], v[146:147] neg_lo:[1,0,0] neg_hi:[1,0,0]
	v_pk_fma_f32 v[148:149], v[98:99], v[156:157], v[148:149] neg_lo:[1,0,0] neg_hi:[1,0,0]
	v_pk_fma_f32 v[150:151], v[100:101], v[158:159], v[150:151] neg_lo:[1,0,0] neg_hi:[1,0,0]
	v_pk_fma_f32 v[152:153], v[102:103], v[160:161], v[152:153] neg_lo:[1,0,0] neg_hi:[1,0,0]
	v_pk_fma_f32 v[146:147], v[104:105], v[162:163], v[146:147] neg_lo:[1,0,0] neg_hi:[1,0,0]
	v_pk_fma_f32 v[148:149], v[106:107], v[164:165], v[148:149] neg_lo:[1,0,0] neg_hi:[1,0,0]
	v_pk_fma_f32 v[150:151], v[108:109], v[166:167], v[150:151] neg_lo:[1,0,0] neg_hi:[1,0,0]
	v_pk_fma_f32 v[152:153], v[110:111], v[168:169], v[152:153] neg_lo:[1,0,0] neg_hi:[1,0,0]
	v_pk_add_f32 v[146:147], v[146:147], v[150:151]
	v_pk_add_f32 v[148:149], v[148:149], v[152:153]
	v_add_f32_e32 v146, v147, v146
	v_add_f32_e32 v148, v148, v149
	v_add_f32_e32 v176, v148, v146
	ds_read_b128 v[80:83], v197 offset:1024
	ds_read_b128 v[84:87], v197 offset:1040
	ds_read_b128 v[88:91], v197 offset:1056
	ds_read_b128 v[92:95], v197 offset:1072
	ds_read_b128 v[96:99], v197 offset:1088
	ds_read_b128 v[100:103], v197 offset:1104
	ds_read_b128 v[104:107], v197 offset:1120
	s_waitcnt lgkmcnt(14)
	ds_read_b128 v[108:111], v197 offset:1136
	s_waitcnt lgkmcnt(12)
	v_pk_fma_f32 v[146:147], v[112:113], v[64:65], v[200:201] neg_lo:[1,0,0] neg_hi:[1,0,0]
	v_pk_fma_f32 v[148:149], v[114:115], v[66:67], v[200:201] neg_lo:[1,0,0] neg_hi:[1,0,0]
	v_pk_fma_f32 v[150:151], v[116:117], v[68:69], v[200:201] neg_lo:[1,0,0] neg_hi:[1,0,0]
	v_pk_fma_f32 v[152:153], v[118:119], v[70:71], v[200:201] neg_lo:[1,0,0] neg_hi:[1,0,0]
	v_pk_fma_f32 v[146:147], v[120:121], v[72:73], v[146:147] neg_lo:[1,0,0] neg_hi:[1,0,0]
	v_pk_fma_f32 v[148:149], v[122:123], v[74:75], v[148:149] neg_lo:[1,0,0] neg_hi:[1,0,0]
	v_pk_fma_f32 v[150:151], v[124:125], v[76:77], v[150:151] neg_lo:[1,0,0] neg_hi:[1,0,0]
	v_pk_fma_f32 v[152:153], v[126:127], v[78:79], v[152:153] neg_lo:[1,0,0] neg_hi:[1,0,0]
	s_waitcnt lgkmcnt(8)
	v_pk_fma_f32 v[146:147], v[130:131], v[154:155], v[146:147] neg_lo:[1,0,0] neg_hi:[1,0,0]
	v_pk_fma_f32 v[148:149], v[132:133], v[156:157], v[148:149] neg_lo:[1,0,0] neg_hi:[1,0,0]
	v_pk_fma_f32 v[150:151], v[134:135], v[158:159], v[150:151] neg_lo:[1,0,0] neg_hi:[1,0,0]
	v_pk_fma_f32 v[152:153], v[136:137], v[160:161], v[152:153] neg_lo:[1,0,0] neg_hi:[1,0,0]
	v_pk_fma_f32 v[146:147], v[138:139], v[162:163], v[146:147] neg_lo:[1,0,0] neg_hi:[1,0,0]
	v_pk_fma_f32 v[148:149], v[140:141], v[164:165], v[148:149] neg_lo:[1,0,0] neg_hi:[1,0,0]
	v_pk_fma_f32 v[150:151], v[142:143], v[166:167], v[150:151] neg_lo:[1,0,0] neg_hi:[1,0,0]
	v_pk_fma_f32 v[152:153], v[144:145], v[168:169], v[152:153] neg_lo:[1,0,0] neg_hi:[1,0,0]
	v_pk_add_f32 v[146:147], v[146:147], v[150:151]
	v_pk_add_f32 v[148:149], v[148:149], v[152:153]
	v_add_f32_e32 v146, v147, v146
	v_add_f32_e32 v148, v148, v149
	v_add_f32_e32 v177, v148, v146
	ds_read_b128 v[112:115], v197 offset:1152
	ds_read_b128 v[116:119], v197 offset:1168
	ds_read_b128 v[120:123], v197 offset:1184
	ds_read_b128 v[124:127], v197 offset:1200
	ds_read_b128 v[130:133], v197 offset:1216
	ds_read_b128 v[134:137], v197 offset:1232
	ds_read_b128 v[138:141], v197 offset:1248
	s_waitcnt lgkmcnt(14)
	ds_read_b128 v[142:145], v197 offset:1264
	s_waitcnt lgkmcnt(12)
	v_pk_fma_f32 v[146:147], v[80:81], v[64:65], v[200:201] neg_lo:[1,0,0] neg_hi:[1,0,0]
	v_pk_fma_f32 v[148:149], v[82:83], v[66:67], v[200:201] neg_lo:[1,0,0] neg_hi:[1,0,0]
	v_pk_fma_f32 v[150:151], v[84:85], v[68:69], v[200:201] neg_lo:[1,0,0] neg_hi:[1,0,0]
	v_pk_fma_f32 v[152:153], v[86:87], v[70:71], v[200:201] neg_lo:[1,0,0] neg_hi:[1,0,0]
	v_pk_fma_f32 v[146:147], v[88:89], v[72:73], v[146:147] neg_lo:[1,0,0] neg_hi:[1,0,0]
	v_pk_fma_f32 v[148:149], v[90:91], v[74:75], v[148:149] neg_lo:[1,0,0] neg_hi:[1,0,0]
	v_pk_fma_f32 v[150:151], v[92:93], v[76:77], v[150:151] neg_lo:[1,0,0] neg_hi:[1,0,0]
	v_pk_fma_f32 v[152:153], v[94:95], v[78:79], v[152:153] neg_lo:[1,0,0] neg_hi:[1,0,0]
	s_waitcnt lgkmcnt(8)
	v_pk_fma_f32 v[146:147], v[96:97], v[154:155], v[146:147] neg_lo:[1,0,0] neg_hi:[1,0,0]
	v_pk_fma_f32 v[148:149], v[98:99], v[156:157], v[148:149] neg_lo:[1,0,0] neg_hi:[1,0,0]
	v_pk_fma_f32 v[150:151], v[100:101], v[158:159], v[150:151] neg_lo:[1,0,0] neg_hi:[1,0,0]
	v_pk_fma_f32 v[152:153], v[102:103], v[160:161], v[152:153] neg_lo:[1,0,0] neg_hi:[1,0,0]
	v_pk_fma_f32 v[146:147], v[104:105], v[162:163], v[146:147] neg_lo:[1,0,0] neg_hi:[1,0,0]
	v_pk_fma_f32 v[148:149], v[106:107], v[164:165], v[148:149] neg_lo:[1,0,0] neg_hi:[1,0,0]
	v_pk_fma_f32 v[150:151], v[108:109], v[166:167], v[150:151] neg_lo:[1,0,0] neg_hi:[1,0,0]
	v_pk_fma_f32 v[152:153], v[110:111], v[168:169], v[152:153] neg_lo:[1,0,0] neg_hi:[1,0,0]
	v_pk_add_f32 v[146:147], v[146:147], v[150:151]
	v_pk_add_f32 v[148:149], v[148:149], v[152:153]
	v_add_f32_e32 v146, v147, v146
	v_add_f32_e32 v148, v148, v149
	v_add_f32_e32 v178, v148, v146
	ds_read_b128 v[80:83], v197 offset:1280
	ds_read_b128 v[84:87], v197 offset:1296
	ds_read_b128 v[88:91], v197 offset:1312
	ds_read_b128 v[92:95], v197 offset:1328
	ds_read_b128 v[96:99], v197 offset:1344
	ds_read_b128 v[100:103], v197 offset:1360
	ds_read_b128 v[104:107], v197 offset:1376
	s_waitcnt lgkmcnt(14)
	ds_read_b128 v[108:111], v197 offset:1392
	s_waitcnt lgkmcnt(12)
	v_pk_fma_f32 v[146:147], v[112:113], v[64:65], v[200:201] neg_lo:[1,0,0] neg_hi:[1,0,0]
	v_pk_fma_f32 v[148:149], v[114:115], v[66:67], v[200:201] neg_lo:[1,0,0] neg_hi:[1,0,0]
	v_pk_fma_f32 v[150:151], v[116:117], v[68:69], v[200:201] neg_lo:[1,0,0] neg_hi:[1,0,0]
	v_pk_fma_f32 v[152:153], v[118:119], v[70:71], v[200:201] neg_lo:[1,0,0] neg_hi:[1,0,0]
	v_pk_fma_f32 v[146:147], v[120:121], v[72:73], v[146:147] neg_lo:[1,0,0] neg_hi:[1,0,0]
	v_pk_fma_f32 v[148:149], v[122:123], v[74:75], v[148:149] neg_lo:[1,0,0] neg_hi:[1,0,0]
	v_pk_fma_f32 v[150:151], v[124:125], v[76:77], v[150:151] neg_lo:[1,0,0] neg_hi:[1,0,0]
	v_pk_fma_f32 v[152:153], v[126:127], v[78:79], v[152:153] neg_lo:[1,0,0] neg_hi:[1,0,0]
	s_waitcnt lgkmcnt(8)
	v_pk_fma_f32 v[146:147], v[130:131], v[154:155], v[146:147] neg_lo:[1,0,0] neg_hi:[1,0,0]
	v_pk_fma_f32 v[148:149], v[132:133], v[156:157], v[148:149] neg_lo:[1,0,0] neg_hi:[1,0,0]
	v_pk_fma_f32 v[150:151], v[134:135], v[158:159], v[150:151] neg_lo:[1,0,0] neg_hi:[1,0,0]
	v_pk_fma_f32 v[152:153], v[136:137], v[160:161], v[152:153] neg_lo:[1,0,0] neg_hi:[1,0,0]
	v_pk_fma_f32 v[146:147], v[138:139], v[162:163], v[146:147] neg_lo:[1,0,0] neg_hi:[1,0,0]
	v_pk_fma_f32 v[148:149], v[140:141], v[164:165], v[148:149] neg_lo:[1,0,0] neg_hi:[1,0,0]
	v_pk_fma_f32 v[150:151], v[142:143], v[166:167], v[150:151] neg_lo:[1,0,0] neg_hi:[1,0,0]
	v_pk_fma_f32 v[152:153], v[144:145], v[168:169], v[152:153] neg_lo:[1,0,0] neg_hi:[1,0,0]
	v_pk_add_f32 v[146:147], v[146:147], v[150:151]
	v_pk_add_f32 v[148:149], v[148:149], v[152:153]
	v_add_f32_e32 v146, v147, v146
	v_add_f32_e32 v148, v148, v149
	v_add_f32_e32 v179, v148, v146
	ds_read_b128 v[112:115], v197 offset:1408
	ds_read_b128 v[116:119], v197 offset:1424
	ds_read_b128 v[120:123], v197 offset:1440
	ds_read_b128 v[124:127], v197 offset:1456
	ds_read_b128 v[130:133], v197 offset:1472
	ds_read_b128 v[134:137], v197 offset:1488
	ds_read_b128 v[138:141], v197 offset:1504
	s_waitcnt lgkmcnt(14)
	ds_read_b128 v[142:145], v197 offset:1520
	s_waitcnt lgkmcnt(12)
	v_pk_fma_f32 v[146:147], v[80:81], v[64:65], v[200:201] neg_lo:[1,0,0] neg_hi:[1,0,0]
	v_pk_fma_f32 v[148:149], v[82:83], v[66:67], v[200:201] neg_lo:[1,0,0] neg_hi:[1,0,0]
	v_pk_fma_f32 v[150:151], v[84:85], v[68:69], v[200:201] neg_lo:[1,0,0] neg_hi:[1,0,0]
	v_pk_fma_f32 v[152:153], v[86:87], v[70:71], v[200:201] neg_lo:[1,0,0] neg_hi:[1,0,0]
	v_pk_fma_f32 v[146:147], v[88:89], v[72:73], v[146:147] neg_lo:[1,0,0] neg_hi:[1,0,0]
	v_pk_fma_f32 v[148:149], v[90:91], v[74:75], v[148:149] neg_lo:[1,0,0] neg_hi:[1,0,0]
	v_pk_fma_f32 v[150:151], v[92:93], v[76:77], v[150:151] neg_lo:[1,0,0] neg_hi:[1,0,0]
	v_pk_fma_f32 v[152:153], v[94:95], v[78:79], v[152:153] neg_lo:[1,0,0] neg_hi:[1,0,0]
	s_waitcnt lgkmcnt(8)
	v_pk_fma_f32 v[146:147], v[96:97], v[154:155], v[146:147] neg_lo:[1,0,0] neg_hi:[1,0,0]
	v_pk_fma_f32 v[148:149], v[98:99], v[156:157], v[148:149] neg_lo:[1,0,0] neg_hi:[1,0,0]
	v_pk_fma_f32 v[150:151], v[100:101], v[158:159], v[150:151] neg_lo:[1,0,0] neg_hi:[1,0,0]
	v_pk_fma_f32 v[152:153], v[102:103], v[160:161], v[152:153] neg_lo:[1,0,0] neg_hi:[1,0,0]
	v_pk_fma_f32 v[146:147], v[104:105], v[162:163], v[146:147] neg_lo:[1,0,0] neg_hi:[1,0,0]
	v_pk_fma_f32 v[148:149], v[106:107], v[164:165], v[148:149] neg_lo:[1,0,0] neg_hi:[1,0,0]
	v_pk_fma_f32 v[150:151], v[108:109], v[166:167], v[150:151] neg_lo:[1,0,0] neg_hi:[1,0,0]
	v_pk_fma_f32 v[152:153], v[110:111], v[168:169], v[152:153] neg_lo:[1,0,0] neg_hi:[1,0,0]
	v_pk_add_f32 v[146:147], v[146:147], v[150:151]
	v_pk_add_f32 v[148:149], v[148:149], v[152:153]
	v_add_f32_e32 v146, v147, v146
	v_add_f32_e32 v148, v148, v149
	v_add_f32_e32 v180, v148, v146
	ds_read_b128 v[80:83], v197 offset:1536
	ds_read_b128 v[84:87], v197 offset:1552
	ds_read_b128 v[88:91], v197 offset:1568
	ds_read_b128 v[92:95], v197 offset:1584
	ds_read_b128 v[96:99], v197 offset:1600
	ds_read_b128 v[100:103], v197 offset:1616
	ds_read_b128 v[104:107], v197 offset:1632
	s_waitcnt lgkmcnt(14)
	ds_read_b128 v[108:111], v197 offset:1648
	s_waitcnt lgkmcnt(12)
	v_pk_fma_f32 v[146:147], v[112:113], v[64:65], v[200:201] neg_lo:[1,0,0] neg_hi:[1,0,0]
	v_pk_fma_f32 v[148:149], v[114:115], v[66:67], v[200:201] neg_lo:[1,0,0] neg_hi:[1,0,0]
	v_pk_fma_f32 v[150:151], v[116:117], v[68:69], v[200:201] neg_lo:[1,0,0] neg_hi:[1,0,0]
	v_pk_fma_f32 v[152:153], v[118:119], v[70:71], v[200:201] neg_lo:[1,0,0] neg_hi:[1,0,0]
	v_pk_fma_f32 v[146:147], v[120:121], v[72:73], v[146:147] neg_lo:[1,0,0] neg_hi:[1,0,0]
	v_pk_fma_f32 v[148:149], v[122:123], v[74:75], v[148:149] neg_lo:[1,0,0] neg_hi:[1,0,0]
	v_pk_fma_f32 v[150:151], v[124:125], v[76:77], v[150:151] neg_lo:[1,0,0] neg_hi:[1,0,0]
	v_pk_fma_f32 v[152:153], v[126:127], v[78:79], v[152:153] neg_lo:[1,0,0] neg_hi:[1,0,0]
	s_waitcnt lgkmcnt(8)
	v_pk_fma_f32 v[146:147], v[130:131], v[154:155], v[146:147] neg_lo:[1,0,0] neg_hi:[1,0,0]
	v_pk_fma_f32 v[148:149], v[132:133], v[156:157], v[148:149] neg_lo:[1,0,0] neg_hi:[1,0,0]
	v_pk_fma_f32 v[150:151], v[134:135], v[158:159], v[150:151] neg_lo:[1,0,0] neg_hi:[1,0,0]
	v_pk_fma_f32 v[152:153], v[136:137], v[160:161], v[152:153] neg_lo:[1,0,0] neg_hi:[1,0,0]
	v_pk_fma_f32 v[146:147], v[138:139], v[162:163], v[146:147] neg_lo:[1,0,0] neg_hi:[1,0,0]
	v_pk_fma_f32 v[148:149], v[140:141], v[164:165], v[148:149] neg_lo:[1,0,0] neg_hi:[1,0,0]
	v_pk_fma_f32 v[150:151], v[142:143], v[166:167], v[150:151] neg_lo:[1,0,0] neg_hi:[1,0,0]
	v_pk_fma_f32 v[152:153], v[144:145], v[168:169], v[152:153] neg_lo:[1,0,0] neg_hi:[1,0,0]
	v_pk_add_f32 v[146:147], v[146:147], v[150:151]
	v_pk_add_f32 v[148:149], v[148:149], v[152:153]
	v_add_f32_e32 v146, v147, v146
	v_add_f32_e32 v148, v148, v149
	v_add_f32_e32 v181, v148, v146
	ds_read_b128 v[112:115], v197 offset:1664
	ds_read_b128 v[116:119], v197 offset:1680
	ds_read_b128 v[120:123], v197 offset:1696
	ds_read_b128 v[124:127], v197 offset:1712
	ds_read_b128 v[130:133], v197 offset:1728
	ds_read_b128 v[134:137], v197 offset:1744
	ds_read_b128 v[138:141], v197 offset:1760
	s_waitcnt lgkmcnt(14)
	ds_read_b128 v[142:145], v197 offset:1776
	s_waitcnt lgkmcnt(12)
	v_pk_fma_f32 v[146:147], v[80:81], v[64:65], v[200:201] neg_lo:[1,0,0] neg_hi:[1,0,0]
	v_pk_fma_f32 v[148:149], v[82:83], v[66:67], v[200:201] neg_lo:[1,0,0] neg_hi:[1,0,0]
	v_pk_fma_f32 v[150:151], v[84:85], v[68:69], v[200:201] neg_lo:[1,0,0] neg_hi:[1,0,0]
	v_pk_fma_f32 v[152:153], v[86:87], v[70:71], v[200:201] neg_lo:[1,0,0] neg_hi:[1,0,0]
	v_pk_fma_f32 v[146:147], v[88:89], v[72:73], v[146:147] neg_lo:[1,0,0] neg_hi:[1,0,0]
	v_pk_fma_f32 v[148:149], v[90:91], v[74:75], v[148:149] neg_lo:[1,0,0] neg_hi:[1,0,0]
	v_pk_fma_f32 v[150:151], v[92:93], v[76:77], v[150:151] neg_lo:[1,0,0] neg_hi:[1,0,0]
	v_pk_fma_f32 v[152:153], v[94:95], v[78:79], v[152:153] neg_lo:[1,0,0] neg_hi:[1,0,0]
	s_waitcnt lgkmcnt(8)
	v_pk_fma_f32 v[146:147], v[96:97], v[154:155], v[146:147] neg_lo:[1,0,0] neg_hi:[1,0,0]
	v_pk_fma_f32 v[148:149], v[98:99], v[156:157], v[148:149] neg_lo:[1,0,0] neg_hi:[1,0,0]
	v_pk_fma_f32 v[150:151], v[100:101], v[158:159], v[150:151] neg_lo:[1,0,0] neg_hi:[1,0,0]
	v_pk_fma_f32 v[152:153], v[102:103], v[160:161], v[152:153] neg_lo:[1,0,0] neg_hi:[1,0,0]
	v_pk_fma_f32 v[146:147], v[104:105], v[162:163], v[146:147] neg_lo:[1,0,0] neg_hi:[1,0,0]
	v_pk_fma_f32 v[148:149], v[106:107], v[164:165], v[148:149] neg_lo:[1,0,0] neg_hi:[1,0,0]
	v_pk_fma_f32 v[150:151], v[108:109], v[166:167], v[150:151] neg_lo:[1,0,0] neg_hi:[1,0,0]
	v_pk_fma_f32 v[152:153], v[110:111], v[168:169], v[152:153] neg_lo:[1,0,0] neg_hi:[1,0,0]
	v_pk_add_f32 v[146:147], v[146:147], v[150:151]
	v_pk_add_f32 v[148:149], v[148:149], v[152:153]
	v_add_f32_e32 v146, v147, v146
	v_add_f32_e32 v148, v148, v149
	v_add_f32_e32 v182, v148, v146
	ds_read_b128 v[80:83], v197 offset:1792
	ds_read_b128 v[84:87], v197 offset:1808
	ds_read_b128 v[88:91], v197 offset:1824
	ds_read_b128 v[92:95], v197 offset:1840
	ds_read_b128 v[96:99], v197 offset:1856
	ds_read_b128 v[100:103], v197 offset:1872
	ds_read_b128 v[104:107], v197 offset:1888
	s_waitcnt lgkmcnt(14)
	ds_read_b128 v[108:111], v197 offset:1904
	s_waitcnt lgkmcnt(12)
	v_pk_fma_f32 v[146:147], v[112:113], v[64:65], v[200:201] neg_lo:[1,0,0] neg_hi:[1,0,0]
	v_pk_fma_f32 v[148:149], v[114:115], v[66:67], v[200:201] neg_lo:[1,0,0] neg_hi:[1,0,0]
	v_pk_fma_f32 v[150:151], v[116:117], v[68:69], v[200:201] neg_lo:[1,0,0] neg_hi:[1,0,0]
	v_pk_fma_f32 v[152:153], v[118:119], v[70:71], v[200:201] neg_lo:[1,0,0] neg_hi:[1,0,0]
	v_pk_fma_f32 v[146:147], v[120:121], v[72:73], v[146:147] neg_lo:[1,0,0] neg_hi:[1,0,0]
	v_pk_fma_f32 v[148:149], v[122:123], v[74:75], v[148:149] neg_lo:[1,0,0] neg_hi:[1,0,0]
	v_pk_fma_f32 v[150:151], v[124:125], v[76:77], v[150:151] neg_lo:[1,0,0] neg_hi:[1,0,0]
	v_pk_fma_f32 v[152:153], v[126:127], v[78:79], v[152:153] neg_lo:[1,0,0] neg_hi:[1,0,0]
	s_waitcnt lgkmcnt(8)
	v_pk_fma_f32 v[146:147], v[130:131], v[154:155], v[146:147] neg_lo:[1,0,0] neg_hi:[1,0,0]
	v_pk_fma_f32 v[148:149], v[132:133], v[156:157], v[148:149] neg_lo:[1,0,0] neg_hi:[1,0,0]
	v_pk_fma_f32 v[150:151], v[134:135], v[158:159], v[150:151] neg_lo:[1,0,0] neg_hi:[1,0,0]
	v_pk_fma_f32 v[152:153], v[136:137], v[160:161], v[152:153] neg_lo:[1,0,0] neg_hi:[1,0,0]
	v_pk_fma_f32 v[146:147], v[138:139], v[162:163], v[146:147] neg_lo:[1,0,0] neg_hi:[1,0,0]
	v_pk_fma_f32 v[148:149], v[140:141], v[164:165], v[148:149] neg_lo:[1,0,0] neg_hi:[1,0,0]
	v_pk_fma_f32 v[150:151], v[142:143], v[166:167], v[150:151] neg_lo:[1,0,0] neg_hi:[1,0,0]
	v_pk_fma_f32 v[152:153], v[144:145], v[168:169], v[152:153] neg_lo:[1,0,0] neg_hi:[1,0,0]
	v_pk_add_f32 v[146:147], v[146:147], v[150:151]
	v_pk_add_f32 v[148:149], v[148:149], v[152:153]
	v_add_f32_e32 v146, v147, v146
	v_add_f32_e32 v148, v148, v149
	v_add_f32_e32 v183, v148, v146
	ds_read_b128 v[112:115], v197 offset:1920
	ds_read_b128 v[116:119], v197 offset:1936
	ds_read_b128 v[120:123], v197 offset:1952
	ds_read_b128 v[124:127], v197 offset:1968
	ds_read_b128 v[130:133], v197 offset:1984
	ds_read_b128 v[134:137], v197 offset:2000
	ds_read_b128 v[138:141], v197 offset:2016
	s_waitcnt lgkmcnt(14)
	ds_read_b128 v[142:145], v197 offset:2032
	s_waitcnt lgkmcnt(12)
	v_pk_fma_f32 v[146:147], v[80:81], v[64:65], v[200:201] neg_lo:[1,0,0] neg_hi:[1,0,0]
	v_pk_fma_f32 v[148:149], v[82:83], v[66:67], v[200:201] neg_lo:[1,0,0] neg_hi:[1,0,0]
	v_pk_fma_f32 v[150:151], v[84:85], v[68:69], v[200:201] neg_lo:[1,0,0] neg_hi:[1,0,0]
	v_pk_fma_f32 v[152:153], v[86:87], v[70:71], v[200:201] neg_lo:[1,0,0] neg_hi:[1,0,0]
	v_pk_fma_f32 v[146:147], v[88:89], v[72:73], v[146:147] neg_lo:[1,0,0] neg_hi:[1,0,0]
	v_pk_fma_f32 v[148:149], v[90:91], v[74:75], v[148:149] neg_lo:[1,0,0] neg_hi:[1,0,0]
	v_pk_fma_f32 v[150:151], v[92:93], v[76:77], v[150:151] neg_lo:[1,0,0] neg_hi:[1,0,0]
	v_pk_fma_f32 v[152:153], v[94:95], v[78:79], v[152:153] neg_lo:[1,0,0] neg_hi:[1,0,0]
	s_waitcnt lgkmcnt(8)
	v_pk_fma_f32 v[146:147], v[96:97], v[154:155], v[146:147] neg_lo:[1,0,0] neg_hi:[1,0,0]
	v_pk_fma_f32 v[148:149], v[98:99], v[156:157], v[148:149] neg_lo:[1,0,0] neg_hi:[1,0,0]
	v_pk_fma_f32 v[150:151], v[100:101], v[158:159], v[150:151] neg_lo:[1,0,0] neg_hi:[1,0,0]
	v_pk_fma_f32 v[152:153], v[102:103], v[160:161], v[152:153] neg_lo:[1,0,0] neg_hi:[1,0,0]
	v_pk_fma_f32 v[146:147], v[104:105], v[162:163], v[146:147] neg_lo:[1,0,0] neg_hi:[1,0,0]
	v_pk_fma_f32 v[148:149], v[106:107], v[164:165], v[148:149] neg_lo:[1,0,0] neg_hi:[1,0,0]
	v_pk_fma_f32 v[150:151], v[108:109], v[166:167], v[150:151] neg_lo:[1,0,0] neg_hi:[1,0,0]
	v_pk_fma_f32 v[152:153], v[110:111], v[168:169], v[152:153] neg_lo:[1,0,0] neg_hi:[1,0,0]
	v_pk_add_f32 v[146:147], v[146:147], v[150:151]
	v_pk_add_f32 v[148:149], v[148:149], v[152:153]
	v_add_f32_e32 v146, v147, v146
	v_add_f32_e32 v148, v148, v149
	v_add_f32_e32 v184, v148, v146
	s_waitcnt lgkmcnt(4)
	v_pk_fma_f32 v[146:147], v[112:113], v[64:65], v[200:201] neg_lo:[1,0,0] neg_hi:[1,0,0]
	v_pk_fma_f32 v[148:149], v[114:115], v[66:67], v[200:201] neg_lo:[1,0,0] neg_hi:[1,0,0]
	v_pk_fma_f32 v[150:151], v[116:117], v[68:69], v[200:201] neg_lo:[1,0,0] neg_hi:[1,0,0]
	v_pk_fma_f32 v[152:153], v[118:119], v[70:71], v[200:201] neg_lo:[1,0,0] neg_hi:[1,0,0]
	v_pk_fma_f32 v[146:147], v[120:121], v[72:73], v[146:147] neg_lo:[1,0,0] neg_hi:[1,0,0]
	v_pk_fma_f32 v[148:149], v[122:123], v[74:75], v[148:149] neg_lo:[1,0,0] neg_hi:[1,0,0]
	v_pk_fma_f32 v[150:151], v[124:125], v[76:77], v[150:151] neg_lo:[1,0,0] neg_hi:[1,0,0]
	v_pk_fma_f32 v[152:153], v[126:127], v[78:79], v[152:153] neg_lo:[1,0,0] neg_hi:[1,0,0]
	s_waitcnt lgkmcnt(0)
	v_pk_fma_f32 v[146:147], v[130:131], v[154:155], v[146:147] neg_lo:[1,0,0] neg_hi:[1,0,0]
	v_pk_fma_f32 v[148:149], v[132:133], v[156:157], v[148:149] neg_lo:[1,0,0] neg_hi:[1,0,0]
	v_pk_fma_f32 v[150:151], v[134:135], v[158:159], v[150:151] neg_lo:[1,0,0] neg_hi:[1,0,0]
	v_pk_fma_f32 v[152:153], v[136:137], v[160:161], v[152:153] neg_lo:[1,0,0] neg_hi:[1,0,0]
	v_pk_fma_f32 v[146:147], v[138:139], v[162:163], v[146:147] neg_lo:[1,0,0] neg_hi:[1,0,0]
	v_pk_fma_f32 v[148:149], v[140:141], v[164:165], v[148:149] neg_lo:[1,0,0] neg_hi:[1,0,0]
	v_pk_fma_f32 v[150:151], v[142:143], v[166:167], v[150:151] neg_lo:[1,0,0] neg_hi:[1,0,0]
	v_pk_fma_f32 v[152:153], v[144:145], v[168:169], v[152:153] neg_lo:[1,0,0] neg_hi:[1,0,0]
	v_pk_add_f32 v[146:147], v[146:147], v[150:151]
	v_pk_add_f32 v[148:149], v[148:149], v[152:153]
	v_add_f32_e32 v146, v147, v146
	v_add_f32_e32 v148, v148, v149
	v_add_f32_e32 v185, v148, v146
	s_cmp_lg_u32 s87, 0
	s_cbranch_scc1 .Ltri2_wb_b
	v_add_u32_e32 v204, v195, v199
	v_add_u32_e32 v205, v196, v199
	ds_write_b32 v204, v0
	ds_write_b32 v204, v1 offset:272
	ds_write_b32 v204, v2 offset:544
	ds_write_b32 v204, v3 offset:816
	ds_write_b32 v204, v4 offset:1088
	ds_write_b32 v204, v5 offset:1360
	ds_write_b32 v204, v6 offset:1632
	ds_write_b32 v204, v7 offset:1904
	ds_write_b32 v204, v8 offset:2176
	ds_write_b32 v204, v9 offset:2448
	ds_write_b32 v204, v10 offset:2720
	ds_write_b32 v204, v11 offset:2992
	ds_write_b32 v204, v12 offset:3264
	ds_write_b32 v204, v13 offset:3536
	ds_write_b32 v204, v14 offset:3808
	ds_write_b32 v204, v15 offset:4080
	ds_write_b32 v204, v16 offset:4352
	ds_write_b32 v204, v17 offset:4624
	ds_write_b32 v204, v18 offset:4896
	ds_write_b32 v204, v19 offset:5168
	ds_write_b32 v204, v20 offset:5440
	ds_write_b32 v204, v21 offset:5712
	ds_write_b32 v204, v22 offset:5984
	ds_write_b32 v204, v23 offset:6256
	ds_write_b32 v204, v24 offset:6528
	ds_write_b32 v204, v25 offset:6800
	ds_write_b32 v204, v26 offset:7072
	ds_write_b32 v204, v27 offset:7344
	ds_write_b32 v204, v28 offset:7616
	ds_write_b32 v204, v29 offset:7888
	ds_write_b32 v204, v30 offset:8160
	ds_write_b32 v204, v31 offset:8432
	ds_write_b32 v205, v170
	ds_write_b32 v205, v171 offset:272
	ds_write_b32 v205, v172 offset:544
	ds_write_b32 v205, v173 offset:816
	ds_write_b32 v205, v174 offset:1088
	ds_write_b32 v205, v175 offset:1360
	ds_write_b32 v205, v176 offset:1632
	ds_write_b32 v205, v177 offset:1904
	ds_write_b32 v205, v178 offset:2176
	ds_write_b32 v205, v179 offset:2448
	ds_write_b32 v205, v180 offset:2720
	ds_write_b32 v205, v181 offset:2992
	ds_write_b32 v205, v182 offset:3264
	ds_write_b32 v205, v183 offset:3536
	ds_write_b32 v205, v184 offset:3808
	ds_write_b32 v205, v185 offset:4080
	s_branch .Ltri2_wb_done

.LBB0_562:
	v_readlane_b32 s4, v252, 20
	v_readlane_b32 s5, v252, 21
	v_readlane_b32 s1, v253, 63
	s_mov_b64 s[6:7], -1
	s_waitcnt lgkmcnt(0)
	s_nop 1
	global_load_dword v0, v129, s[4:5] sc1
	v_readlane_b32 s4, v252, 22
	v_readlane_b32 s5, v252, 23
	s_nop 4
	global_load_dword v1, v129, s[4:5] sc1
	v_readlane_b32 s4, v252, 24
	v_readlane_b32 s5, v252, 25
	s_nop 4
	global_load_dword v2, v129, s[4:5] sc1
	v_readlane_b32 s4, v252, 26
	v_readlane_b32 s5, v252, 27
	s_nop 4
	global_load_dword v3, v129, s[4:5] sc1
	v_readlane_b32 s4, v252, 28
	v_readlane_b32 s5, v252, 29
	s_nop 4
	global_load_dword v4, v129, s[4:5] sc1
	v_readlane_b32 s4, v252, 30
	v_readlane_b32 s5, v252, 31
	s_nop 4
	global_load_dword v5, v129, s[4:5] sc1
	v_readlane_b32 s4, v252, 32
	v_readlane_b32 s5, v252, 33
	s_nop 4
	global_load_dword v6, v129, s[4:5] sc1
	v_readlane_b32 s4, v252, 34
	v_readlane_b32 s5, v252, 35
	s_nop 4
	global_load_dword v7, v129, s[4:5] sc1
	v_readlane_b32 s4, v252, 36
	v_readlane_b32 s5, v252, 37
	s_nop 4
	global_load_dword v8, v129, s[4:5] sc1
	v_readlane_b32 s4, v252, 38
	v_readlane_b32 s5, v252, 39
	s_nop 4
	global_load_dword v9, v129, s[4:5] sc1
	v_readlane_b32 s4, v252, 40
	v_readlane_b32 s5, v252, 41
	s_nop 4
	global_load_dword v10, v129, s[4:5] sc1
	v_readlane_b32 s4, v252, 42
	v_readlane_b32 s5, v252, 43
	s_nop 4
	global_load_dword v11, v129, s[4:5] sc1
	v_readlane_b32 s4, v252, 44
	v_readlane_b32 s5, v252, 45
	s_nop 4
	global_load_dword v12, v129, s[4:5] sc1
	v_readlane_b32 s4, v252, 46
	v_readlane_b32 s5, v252, 47
	s_nop 4
	global_load_dword v13, v129, s[4:5] sc1
	v_readlane_b32 s4, v252, 48
	v_readlane_b32 s5, v252, 49
	s_nop 4
	global_load_dword v14, v129, s[4:5] sc1
	v_readlane_b32 s4, v252, 50
	v_readlane_b32 s5, v252, 51
	s_nop 4
	global_load_dword v15, v129, s[4:5] sc1
	s_mov_b64 s[4:5], -1
	s_waitcnt vmcnt(0)
	v_add_u32_e32 v16, v1, v0
	v_add_u32_e32 v16, v16, v2
	v_add_u32_e32 v16, v16, v3
	v_add_u32_e32 v16, v16, v4
	v_add_u32_e32 v16, v16, v5
	v_add_u32_e32 v16, v16, v6
	v_add_u32_e32 v16, v16, v7
	v_add_u32_e32 v16, v16, v8
	v_add_u32_e32 v16, v16, v9
	v_add_u32_e32 v16, v16, v10
	v_add_u32_e32 v16, v16, v11
	v_add_u32_e32 v16, v16, v12
	v_add_u32_e32 v16, v16, v13
	v_add_u32_e32 v16, v16, v14
	v_add_u32_e32 v16, v16, v15
	v_cmp_eq_u32_e32 vcc, s1, v16
	s_cbranch_vccnz .LBB0_561
	s_and_b32 s1, s0, 0xff
	s_cmp_eq_u32 s1, 0
	s_mov_b64 s[8:9], -1
	s_sleep 1
	s_cbranch_scc0 .LBB0_566
	v_readlane_b32 s4, v252, 18
	v_readlane_b32 s5, v252, 19
	s_nop 4
	global_load_dword v16, v129, s[4:5] sc1
	s_waitcnt vmcnt(0)
	v_cmp_eq_u32_e32 vcc, 0, v16
	s_cbranch_vccnz .LBB0_568
	s_mov_b64 s[8:9], 0
	s_mov_b64 s[4:5], -1
